# selection histogram only counts keys at or above a lower bound (min over the 256 lane slots of each slot's running max), fused bin fma
# speedup vs baseline: 1.0288x; 1.0197x over previous
; DI void lds_barrier() { asm volatile("s_waitcnt lgkmcnt(0)" ::: "memory"); __builtin_amdgcn_s_barrier(); asm volatile("" ::: "memory"); }
; DI void selectA_item(const Params& p, int item, int next_item, char* lds, bf16x8 (&qf)[4], float (&wq)[16]) {
;     ...
;   const f32x4 pcv = ((const f32x4*)p.in[I_P])[(size_t)item * 512 + tid];
;   if (tid < 4) { mm[tid * 2] = 0xFFFFFFFFu; mm[tid * 2 + 1] = 0u; }
;   lds_barrier();
;   const bf16* Kt = (const bf16*)(p.ws + WS_IKS) + (size_t)b * 256 * 2048 + lane * 8;
;   {
;     bf16x8 kf[4], kn[4];
; #pragma unroll
;     for (int t = 0; t < 4; ++t) { kf[t] = (bf16x8){0, 0, 0, 0, 0, 0, 0, 0}; kn[t] = kf[t]; }
;     if (wid < ntile) {
; #pragma unroll
;       for (int t = 0; t < 4; ++t) kf[t] = *(const bf16x8*)(Kt + (size_t)wid * 2048 + t * 512);
;     }
;     float lo0 = INFINITY, hi0 = -INFINITY, lo1 = INFINITY, hi1 = -INFINITY;
;     for (int kt = wid; kt < ntile; kt += 8) {
;       if (kt + 8 < ntile) {
; #pragma unroll
;         for (int t = 0; t < 4; ++t) kn[t] = *(const bf16x8*)(Kt + (size_t)(kt + 8) * 2048 + t * 512);
.LBB0_405:
	s_andn2_b64 vcc, exec, s[4:5]
	s_cbranch_vccnz .LBB0_402
	v_readlane_b32 s4, v254, 3
	v_mov_b32_e32 v72, v182
	v_readlane_b32 s5, v254, 4
	s_load_dwordx2 s[4:5], s[4:5], 0x8
	s_ashr_i32 s3, s2, 31
	s_lshl_b64 s[6:7], s[2:3], 9
	v_ashrrev_i32_e32 v73, 31, v72
	v_lshl_add_u64 v[76:77], s[6:7], 0, v[72:73]
	s_waitcnt lgkmcnt(0)
	v_lshl_add_u64 v[0:1], v[76:77], 4, s[4:5]
	global_load_dwordx4 v[16:19], v[0:1], off
	v_cmp_gt_i32_e32 vcc, 4, v72
	s_and_saveexec_b64 s[4:5], vcc
	v_lshl_add_u32 v0, v72, 3, 0
	v_add_u32_e32 v0, 0x24060, v0
	ds_write_b64 v0, v[114:115]
	v_lshl_add_u32 v0, v72, 2, 0
	v_add_u32_e32 v0, 0x25180, v0
	v_mov_b32_e32 v1, -1
	ds_write_b32 v0, v1
	s_or_b64 exec, exec, s[4:5]
	s_ashr_i32 s52, s2, 11
	s_lshl_b32 s2, s2, 2
	s_and_b32 s2, s2, 0x1ffc
	v_writelane_b32 v254, s2, 58
	s_add_i32 s2, s2, 35
	s_waitcnt lgkmcnt(0)
	s_barrier
	v_ashrrev_i32_e32 v68, 6, v72
	s_lshr_b32 s8, s2, 5
	v_and_b32_e32 v67, 63, v72
	v_bfe_u32 v71, v72, 5, 1
	s_ashr_i32 s53, s52, 31
	v_cmp_gt_i32_e32 vcc, s8, v68
	s_and_saveexec_b64 s[2:3], vcc
	s_cbranch_execz .LBB0_415
	s_lshl_b64 s[4:5], s[52:53], 20
	v_readlane_b32 s6, v254, 24
	s_add_u32 s6, s6, s4
	v_readlane_b32 s7, v254, 25
	s_addc_u32 s7, s7, s5
	v_lshlrev_b32_e32 v48, 4, v67
	v_ashrrev_i32_e32 v69, 31, v68
	v_lshl_add_u64 v[0:1], s[6:7], 0, v[48:49]
	v_lshlrev_b64 v[4:5], 12, v[68:69]
	v_lshl_add_u64 v[6:7], v[0:1], 0, v[4:5]
	global_load_dwordx4 v[116:119], v[6:7], off
	global_load_dwordx4 v[62:65], v[6:7], off offset:1024
	global_load_dwordx4 v[58:61], v[6:7], off offset:2048
	global_load_dwordx4 v[54:57], v[6:7], off offset:3072
	v_lshlrev_b32_e32 v6, 7, v68
	v_mov_b32_e32 v48, v49
	v_and_b32_e32 v69, 31, v72
	v_lshl_add_u32 v6, v71, 16, v6
	v_lshl_add_u64 v[4:5], s[4:5], 0, v[4:5]
	v_readlane_b32 s4, v254, 47
	v_mov_b32_e32 v50, v49
	v_mov_b32_e32 v51, v49
	v_mov_b64_e32 v[20:21], v[48:49]
	v_mov_b64_e32 v[24:25], v[48:49]
	v_mov_b64_e32 v[28:29], v[48:49]
	v_lshl_or_b32 v6, v69, 2, v6
	v_lshl_or_b32 v4, v67, 4, v4
	v_readlane_b32 s5, v254, 48
	v_mov_b64_e32 v[22:23], v[50:51]
	v_mov_b64_e32 v[26:27], v[50:51]
	v_mov_b64_e32 v[30:31], v[50:51]
	v_mov_b64_e32 v[52:53], v[50:51]
	v_cmp_gt_u32_e32 vcc, 32, v67
	v_add_u32_e32 v79, 0, v6
	v_lshl_add_u64 v[80:81], s[4:5], 0, v[4:5]
	v_mov_b32_e32 v73, 0xff800000
	v_mov_b32_e32 v83, 0x7f800000
	s_mov_b64 s[4:5], 0
	v_mov_b64_e32 v[50:51], v[48:49]
	v_mov_b32_e32 v75, 0x7f800000
	v_mov_b32_e32 v48, 0xff800000
	v_mov_b32_e32 v84, v68
	v_readfirstlane_b32 s9, v68
	s_add_i32 s10, s9, 8
	s_cmp_lt_i32 s10, s8
	s_cbranch_scc0 .Lsc_p_noA
	global_load_dwordx4 v[20:23], v[80:81], off offset:-2048
	global_load_dwordx4 v[24:27], v[80:81], off offset:-1024
	global_load_dwordx4 v[28:31], v[80:81], off
	global_load_dwordx4 v[50:53], v[80:81], off offset:1024
	s_mov_b64 s[6:7], 0x8000
	v_lshl_add_u64 v[80:81], v[80:81], 0, s[6:7]
	s_add_i32 s10, s9, 16
	s_cmp_lt_i32 s10, s8
	s_cbranch_scc0 .Lsc_p_noB
	global_load_dwordx4 v[120:123], v[80:81], off offset:-2048
	global_load_dwordx4 v[124:127], v[80:81], off offset:-1024
	global_load_dwordx4 v[128:131], v[80:81], off
	global_load_dwordx4 v[132:135], v[80:81], off offset:1024
	s_mov_b64 s[6:7], 0x8000
	v_lshl_add_u64 v[80:81], v[80:81], 0, s[6:7]
	s_waitcnt vmcnt(8)
	s_branch .Lsc_pre2

; DI unsigned f2ord(float f) { f += 0.f; const unsigned u = __float_as_uint(f); return (u & 0x80000000u) ? ~u : (u | 0x80000000u); }
; DI void selectA_item(const Params& p, int item, int next_item, char* lds, bf16x8 (&qf)[4], float (&wq)[16]) {
;     ...
;     if (wid < ntile) {
; #pragma unroll
;       for (int o = 1; o < 32; o <<= 1) { lo0 = fminf(lo0, __shfl_xor(lo0, o)); hi0 = fmaxf(hi0, __shfl_xor(hi0, o)); lo1 = fminf(lo1, __shfl_xor(lo1, o)); hi1 = fmaxf(hi1, __shfl_xor(hi1, o)); }
;       if (r32 == 0) { atomicMin(&mm[(2 * h) * 2], f2ord(lo0)); atomicMax(&mm[(2 * h) * 2 + 1], f2ord(hi0)); atomicMin(&mm[(2 * h + 1) * 2], f2ord(lo1)); atomicMax(&mm[(2 * h + 1) * 2 + 1], f2ord(hi1)); }
;     }
.Lsc_exit:
	v_and_b32_e32 v0, 64, v183
	v_add_u32_e32 v3, 64, v0
	v_xor_b32_e32 v0, 1, v183
	v_cmp_lt_i32_e32 vcc, v0, v3
	v_max_f32_e32 v4, v83, v83
	v_max_f32_e32 v5, v73, v73
	v_cndmask_b32_e32 v0, v183, v0, vcc
	v_lshlrev_b32_e32 v0, 2, v0
	ds_bpermute_b32 v1, v0, v83
	ds_bpermute_b32 v2, v0, v73
	v_max_f32_e32 v7, v48, v48
	s_waitcnt lgkmcnt(1)
	v_max_f32_e32 v1, v1, v1
	v_min_f32_e32 v1, v4, v1
	ds_bpermute_b32 v4, v0, v75
	s_waitcnt lgkmcnt(1)
	v_max_f32_e32 v2, v2, v2
	v_max_f32_e32 v2, v5, v2
	v_max_f32_e32 v5, v75, v75
	ds_bpermute_b32 v0, v0, v48
	s_waitcnt lgkmcnt(1)
	v_max_f32_e32 v4, v4, v4
	v_min_f32_e32 v4, v5, v4
	v_xor_b32_e32 v5, 2, v183
	v_cmp_lt_i32_e32 vcc, v5, v3
	s_waitcnt lgkmcnt(0)
	v_max_f32_e32 v0, v0, v0
	v_max_f32_e32 v0, v7, v0
	v_cndmask_b32_e32 v5, v183, v5, vcc
	v_lshlrev_b32_e32 v5, 2, v5
	ds_bpermute_b32 v6, v5, v1
	ds_bpermute_b32 v8, v5, v2
	ds_bpermute_b32 v7, v5, v4
	ds_bpermute_b32 v5, v5, v0
	s_waitcnt lgkmcnt(3)
	v_max_f32_e32 v6, v6, v6
	v_min_f32_e32 v1, v1, v6
	s_waitcnt lgkmcnt(2)
	v_max_f32_e32 v6, v8, v8
	v_max_f32_e32 v2, v2, v6
	s_waitcnt lgkmcnt(1)
	v_max_f32_e32 v6, v7, v7
	v_min_f32_e32 v4, v4, v6
	v_xor_b32_e32 v6, 4, v183
	v_cmp_lt_i32_e32 vcc, v6, v3
	s_waitcnt lgkmcnt(0)
	v_max_f32_e32 v5, v5, v5
	v_max_f32_e32 v0, v0, v5
	v_cndmask_b32_e32 v6, v183, v6, vcc
	v_lshlrev_b32_e32 v6, 2, v6
	ds_bpermute_b32 v7, v6, v1
	ds_bpermute_b32 v8, v6, v2
	ds_bpermute_b32 v5, v6, v4
	ds_bpermute_b32 v6, v6, v0
	s_waitcnt lgkmcnt(3)
	v_max_f32_e32 v7, v7, v7
	v_min_f32_e32 v1, v1, v7
	s_waitcnt lgkmcnt(2)
	v_max_f32_e32 v7, v8, v8
	v_max_f32_e32 v2, v2, v7
	v_xor_b32_e32 v7, 8, v183
	v_cmp_lt_i32_e32 vcc, v7, v3
	s_waitcnt lgkmcnt(1)
	v_max_f32_e32 v5, v5, v5
	v_min_f32_e32 v4, v4, v5
	v_cndmask_b32_e32 v7, v183, v7, vcc
	v_lshlrev_b32_e32 v7, 2, v7
	ds_bpermute_b32 v8, v7, v1
	s_waitcnt lgkmcnt(1)
	v_max_f32_e32 v5, v6, v6
	ds_bpermute_b32 v6, v7, v2
	v_max_f32_e32 v5, v0, v5
	s_waitcnt lgkmcnt(1)
	v_max_f32_e32 v0, v8, v8
	ds_bpermute_b32 v8, v7, v4
	ds_bpermute_b32 v7, v7, v5
	v_min_f32_e32 v0, v1, v0
	s_waitcnt lgkmcnt(2)
	v_max_f32_e32 v1, v6, v6
	v_max_f32_e32 v1, v2, v1
	s_waitcnt lgkmcnt(1)
	v_max_f32_e32 v2, v8, v8
	v_min_f32_e32 v2, v4, v2
	s_waitcnt lgkmcnt(0)
	v_max_f32_e32 v4, v7, v7
	v_max_f32_e32 v4, v5, v4
	v_xor_b32_e32 v5, 16, v183
	v_cmp_lt_i32_e32 vcc, v5, v3
	s_nop 1
	v_cndmask_b32_e32 v3, v183, v5, vcc
	v_lshlrev_b32_e32 v7, 2, v3
	ds_bpermute_b32 v3, v7, v0
	ds_bpermute_b32 v5, v7, v1
	ds_bpermute_b32 v6, v7, v2
	ds_bpermute_b32 v7, v7, v4
	v_mov_b32_e32 v242, v73
	v_mov_b32_e32 v243, v48
	s_nop 1
	v_min_f32_dpp v242, v242, v242 quad_perm:[1,0,3,2] row_mask:0xf bank_mask:0xf
	v_min_f32_dpp v243, v243, v243 quad_perm:[1,0,3,2] row_mask:0xf bank_mask:0xf
	s_nop 1
	v_min_f32_dpp v242, v242, v242 quad_perm:[2,3,0,1] row_mask:0xf bank_mask:0xf
	v_min_f32_dpp v243, v243, v243 quad_perm:[2,3,0,1] row_mask:0xf bank_mask:0xf
	s_nop 1
	v_min_f32_dpp v242, v242, v242 row_half_mirror row_mask:0xf bank_mask:0xf
	v_min_f32_dpp v243, v243, v243 row_half_mirror row_mask:0xf bank_mask:0xf
	s_nop 1
	v_min_f32_dpp v242, v242, v242 row_mirror row_mask:0xf bank_mask:0xf
	v_min_f32_dpp v243, v243, v243 row_mirror row_mask:0xf bank_mask:0xf
	v_mov_b32_e32 v244, v242
	v_mov_b32_e32 v245, v243
	s_nop 1
	v_permlane16_swap_b32_e32 v242, v244
	v_permlane16_swap_b32_e32 v243, v245
	v_min_f32_e32 v242, v242, v244
	v_min_f32_e32 v243, v243, v245
	v_cmp_eq_u32_e32 vcc, 0, v69
	s_and_b64 exec, exec, vcc
	s_cbranch_execz .LBB0_415
	s_waitcnt lgkmcnt(0)
	v_max_f32_e32 v7, v7, v7
	v_max_f32_e32 v4, v4, v4
	v_max_f32_e32 v8, v4, v7
	v_max_f32_e32 v4, v6, v6
	v_max_f32_e32 v2, v2, v2
	v_min_f32_e32 v9, v2, v4
	v_max_f32_e32 v2, v5, v5
	v_max_f32_e32 v1, v1, v1
	v_max_f32_e32 v2, v1, v2
	v_max_f32_e32 v1, v3, v3
	v_max_f32_e32 v0, v0, v0
	v_min_f32_e32 v3, v0, v1
	v_lshl_add_u32 v0, v71, 4, 0
	v_add_u32_e32 v4, 0x24060, v0
	v_pk_add_f32 v[0:1], v[2:3], 0 op_sel_hi:[1,0]
	s_nop 0
	v_not_b32_e32 v2, v1
	v_or_b32_e32 v3, 0x80000000, v1
	v_cmp_gt_i32_e32 vcc, 0, v1
	s_nop 1
	v_cndmask_b32_e32 v1, v3, v2, vcc
	ds_min_u32 v4, v1
	v_not_b32_e32 v1, v0
	v_or_b32_e32 v2, 0x80000000, v0
	v_cmp_gt_i32_e32 vcc, 0, v0
	s_nop 1
	v_cndmask_b32_e32 v0, v2, v1, vcc
	ds_max_u32 v4, v0 offset:4
	v_pk_add_f32 v[0:1], v[8:9], 0 op_sel_hi:[1,0]
	s_nop 0
	v_not_b32_e32 v2, v1
	v_or_b32_e32 v3, 0x80000000, v1
	v_cmp_gt_i32_e32 vcc, 0, v1
	s_nop 1
	v_cndmask_b32_e32 v1, v3, v2, vcc
	ds_min_u32 v4, v1 offset:8
	v_not_b32_e32 v1, v0
	v_or_b32_e32 v2, 0x80000000, v0
	v_cmp_gt_i32_e32 vcc, 0, v0
	s_nop 1
	v_cndmask_b32_e32 v0, v2, v1, vcc
	ds_max_u32 v4, v0 offset:12
	v_not_b32_e32 v244, v242
	v_or_b32_e32 v245, 0x80000000, v242
	v_cmp_gt_i32_e64 s[8:9], 0, v242
	v_lshl_add_u32 v246, v71, 3, 0
	v_add_u32_e32 v246, 0x25180, v246
	v_cndmask_b32_e64 v244, v245, v244, s[8:9]
	ds_min_u32 v246, v244
	v_not_b32_e32 v244, v243
	v_or_b32_e32 v245, 0x80000000, v243
	v_cmp_gt_i32_e64 s[8:9], 0, v243
	v_lshl_add_u32 v246, v71, 3, 0
	v_add_u32_e32 v246, 0x25180, v246
	v_cndmask_b32_e64 v244, v245, v244, s[8:9]
	ds_min_u32 v246, v244 offset:4

; DI void lds_barrier() { asm volatile("s_waitcnt lgkmcnt(0)" ::: "memory"); __builtin_amdgcn_s_barrier(); asm volatile("" ::: "memory"); }
; DI float ord2f(unsigned k) { return __uint_as_float((k & 0x80000000u) ? (k ^ 0x80000000u) : ~k); }
; DI void selectA_item(const Params& p, int item, int next_item, char* lds, bf16x8 (&qf)[4], float (&wq)[16]) {
;     ...
;     const float lo = ord2f(mm[g * 2]), hi = ord2f(mm[g * 2 + 1]);
;     const float scale = (hi > lo) ? 1023.f / (hi - lo) : 0.f;
;     for (int i = gt; i < 1024; i += 128) histq[i] = 0;
;     if (gt == 0) { mq[0] = 0; mq[6] = 0; }
;     lds_barrier();
;     float uu[64];
; #pragma unroll
;     for (int i = 0; i < 64; ++i) { const int idx = gt + 128 * i; const float v = (idx < n) ? scq[idx] : lo; const float u = (v - lo) * scale; uu[i] = u;
;       if (big && idx < n) { int bb = (int)u; bb = bb > 1023 ? 1023 : bb; atomicAdd(&histq[bb], 1); } }
.Lsel_big:
	s_lshl_b32 s2, s37, 3
	s_add_i32 s2, s2, 0x24060
	v_mov_b32_e32 v0, s2
	ds_read_b64 v[2:3], v0
	s_lshl_b32 s3, s37, 2
	s_add_i32 s3, s3, 0x25180
	v_mov_b32_e32 v1, s3
	ds_read_b32 v7, v1
	v_lshl_add_u32 v241, v183, 2, 0
	v_add_u32_e32 v241, 0x25200, v241
	s_waitcnt lgkmcnt(0)
	v_ashrrev_i32_e32 v1, 31, v7
	v_and_b32_e32 v1, 0x7fffffff, v1
	v_not_b32_e32 v1, v1
	v_xor_b32_e32 v7, v7, v1
	v_ashrrev_i32_e32 v4, 31, v2
	v_ashrrev_i32_e32 v5, 31, v3
	v_and_b32_e32 v4, 0x7fffffff, v4
	v_and_b32_e32 v5, 0x7fffffff, v5
	v_not_b32_e32 v4, v4
	v_not_b32_e32 v5, v5
	v_xor_b32_e32 v192, v2, v4
	v_xor_b32_e32 v5, v3, v5
	v_sub_f32_e32 v6, v5, v192
	v_cmp_gt_f32_e32 vcc, v5, v192
	v_rcp_f32_e32 v6, v6
	s_nop 1
	v_mul_f32_e32 v6, 0x447fc000, v6
	v_cndmask_b32_e32 v193, 0, v6, vcc
	s_nop 0
	v_mul_f32_e32 v194, v192, v193
	v_and_b32_e32 v6, 0x7fffffff, v194
	s_nop 0
	v_fmac_f32_e32 v194, 0xb4800000, v6
	s_nop 0
	v_fma_f32 v240, v7, v193, -v194
.Lsel_B_0:
	s_cmp_lt_u32 s40, 0x400
	s_cbranch_scc1 .Lsel_B_0_part
	ds_read_b32 v8, v181 offset:0
	ds_read_b32 v9, v181 offset:512
	ds_read_b32 v10, v181 offset:1024
	ds_read_b32 v11, v181 offset:1536
	ds_read_b32 v12, v181 offset:2048
	ds_read_b32 v13, v181 offset:2560
	ds_read_b32 v14, v181 offset:3072
	ds_read_b32 v15, v181 offset:3584
	s_waitcnt lgkmcnt(6)
	v_fma_f32 v116, v8, v193, -v194
	v_fma_f32 v117, v9, v193, -v194
	v_cvt_i32_f32_e32 v16, v116
	v_cvt_i32_f32_e32 v17, v117
	v_cmp_ge_f32_e32 vcc, v116, v240
	v_cmp_ge_f32_e64 s[8:9], v117, v240
	v_min_i32_e32 v16, 0x3ff, v16
	v_min_i32_e32 v17, 0x3ff, v17
	v_lshl_add_u32 v16, v16, 2, s41
	v_lshl_add_u32 v17, v17, 2, s41
	v_cndmask_b32_e32 v16, v241, v16, vcc
	v_cndmask_b32_e64 v17, v241, v17, s[8:9]
	ds_add_u32 v16, v206
	ds_add_u32 v17, v206
	s_waitcnt lgkmcnt(6)
	v_fma_f32 v118, v10, v193, -v194
	v_fma_f32 v119, v11, v193, -v194
	v_cvt_i32_f32_e32 v18, v118
	v_cvt_i32_f32_e32 v19, v119
	v_cmp_ge_f32_e32 vcc, v118, v240
	v_cmp_ge_f32_e64 s[8:9], v119, v240
	v_min_i32_e32 v18, 0x3ff, v18
	v_min_i32_e32 v19, 0x3ff, v19
	v_lshl_add_u32 v18, v18, 2, s41
	v_lshl_add_u32 v19, v19, 2, s41
	v_cndmask_b32_e32 v18, v241, v18, vcc
	v_cndmask_b32_e64 v19, v241, v19, s[8:9]
	ds_add_u32 v18, v206
	ds_add_u32 v19, v206
	s_waitcnt lgkmcnt(6)
	v_fma_f32 v120, v12, v193, -v194
	v_fma_f32 v121, v13, v193, -v194
	v_cvt_i32_f32_e32 v20, v120
	v_cvt_i32_f32_e32 v21, v121
	v_cmp_ge_f32_e32 vcc, v120, v240
	v_cmp_ge_f32_e64 s[8:9], v121, v240
	v_min_i32_e32 v20, 0x3ff, v20
	v_min_i32_e32 v21, 0x3ff, v21
	v_lshl_add_u32 v20, v20, 2, s41
	v_lshl_add_u32 v21, v21, 2, s41
	v_cndmask_b32_e32 v20, v241, v20, vcc
	v_cndmask_b32_e64 v21, v241, v21, s[8:9]
	ds_add_u32 v20, v206
	ds_add_u32 v21, v206
	s_waitcnt lgkmcnt(6)
	v_fma_f32 v122, v14, v193, -v194
	v_fma_f32 v123, v15, v193, -v194
	v_cvt_i32_f32_e32 v22, v122
	v_cvt_i32_f32_e32 v23, v123
	v_cmp_ge_f32_e32 vcc, v122, v240
	v_cmp_ge_f32_e64 s[8:9], v123, v240
	v_min_i32_e32 v22, 0x3ff, v22
	v_min_i32_e32 v23, 0x3ff, v23
	v_lshl_add_u32 v22, v22, 2, s41
	v_lshl_add_u32 v23, v23, 2, s41
	v_cndmask_b32_e32 v22, v241, v22, vcc
	v_cndmask_b32_e64 v23, v241, v23, s[8:9]
	ds_add_u32 v22, v206
	ds_add_u32 v23, v206
.Lsel_B_1:
	s_cmp_le_u32 s40, 0x400
	s_cbranch_scc1 .Lsel_B_done
	s_cmp_lt_u32 s40, 0x800
	s_cbranch_scc1 .Lsel_B_1_part
	ds_read_b32 v8, v181 offset:4096
	ds_read_b32 v9, v181 offset:4608
	ds_read_b32 v10, v181 offset:5120
	ds_read_b32 v11, v181 offset:5632
	ds_read_b32 v12, v181 offset:6144
	ds_read_b32 v13, v181 offset:6656
	ds_read_b32 v14, v181 offset:7168
	ds_read_b32 v15, v181 offset:7680
	s_waitcnt lgkmcnt(6)
	v_fma_f32 v124, v8, v193, -v194
	v_fma_f32 v125, v9, v193, -v194
	v_cvt_i32_f32_e32 v16, v124
	v_cvt_i32_f32_e32 v17, v125
	v_cmp_ge_f32_e32 vcc, v124, v240
	v_cmp_ge_f32_e64 s[8:9], v125, v240
	v_min_i32_e32 v16, 0x3ff, v16
	v_min_i32_e32 v17, 0x3ff, v17
	v_lshl_add_u32 v16, v16, 2, s41
	v_lshl_add_u32 v17, v17, 2, s41
	v_cndmask_b32_e32 v16, v241, v16, vcc
	v_cndmask_b32_e64 v17, v241, v17, s[8:9]
	ds_add_u32 v16, v206
	ds_add_u32 v17, v206
	s_waitcnt lgkmcnt(6)
	v_fma_f32 v126, v10, v193, -v194
	v_fma_f32 v127, v11, v193, -v194
	v_cvt_i32_f32_e32 v18, v126
	v_cvt_i32_f32_e32 v19, v127
	v_cmp_ge_f32_e32 vcc, v126, v240
	v_cmp_ge_f32_e64 s[8:9], v127, v240
	v_min_i32_e32 v18, 0x3ff, v18
	v_min_i32_e32 v19, 0x3ff, v19
	v_lshl_add_u32 v18, v18, 2, s41
	v_lshl_add_u32 v19, v19, 2, s41
	v_cndmask_b32_e32 v18, v241, v18, vcc
	v_cndmask_b32_e64 v19, v241, v19, s[8:9]
	ds_add_u32 v18, v206
	ds_add_u32 v19, v206
	s_waitcnt lgkmcnt(6)
	v_fma_f32 v128, v12, v193, -v194
	v_fma_f32 v129, v13, v193, -v194
	v_cvt_i32_f32_e32 v20, v128
	v_cvt_i32_f32_e32 v21, v129
	v_cmp_ge_f32_e32 vcc, v128, v240
	v_cmp_ge_f32_e64 s[8:9], v129, v240
	v_min_i32_e32 v20, 0x3ff, v20
	v_min_i32_e32 v21, 0x3ff, v21
	v_lshl_add_u32 v20, v20, 2, s41
	v_lshl_add_u32 v21, v21, 2, s41
	v_cndmask_b32_e32 v20, v241, v20, vcc
	v_cndmask_b32_e64 v21, v241, v21, s[8:9]
	ds_add_u32 v20, v206
	ds_add_u32 v21, v206
	s_waitcnt lgkmcnt(6)
	v_fma_f32 v130, v14, v193, -v194
	v_fma_f32 v131, v15, v193, -v194
	v_cvt_i32_f32_e32 v22, v130
	v_cvt_i32_f32_e32 v23, v131
	v_cmp_ge_f32_e32 vcc, v130, v240
	v_cmp_ge_f32_e64 s[8:9], v131, v240
	v_min_i32_e32 v22, 0x3ff, v22
	v_min_i32_e32 v23, 0x3ff, v23
	v_lshl_add_u32 v22, v22, 2, s41
	v_lshl_add_u32 v23, v23, 2, s41
	v_cndmask_b32_e32 v22, v241, v22, vcc
	v_cndmask_b32_e64 v23, v241, v23, s[8:9]
	ds_add_u32 v22, v206
	ds_add_u32 v23, v206
; DI void selectA_item(const Params& p, int item, int next_item, char* lds, bf16x8 (&qf)[4], float (&wq)[16]) {
;     ...
; #pragma unroll
;     for (int i = 0; i < 64; ++i) { const int idx = gt + 128 * i; const float v = (idx < n) ? scq[idx] : lo; const float u = (v - lo) * scale; uu[i] = u;
;       if (big && idx < n) { int bb = (int)u; bb = bb > 1023 ? 1023 : bb; atomicAdd(&histq[bb], 1); } }
.Lsel_B_2:
	s_cmp_le_u32 s40, 0x800
	s_cbranch_scc1 .Lsel_B_done
	s_cmp_lt_u32 s40, 0xc00
	s_cbranch_scc1 .Lsel_B_2_part
	ds_read_b32 v8, v181 offset:8192
	ds_read_b32 v9, v181 offset:8704
	ds_read_b32 v10, v181 offset:9216
	ds_read_b32 v11, v181 offset:9728
	ds_read_b32 v12, v181 offset:10240
	ds_read_b32 v13, v181 offset:10752
	ds_read_b32 v14, v181 offset:11264
	ds_read_b32 v15, v181 offset:11776
	s_waitcnt lgkmcnt(6)
	v_fma_f32 v132, v8, v193, -v194
	v_fma_f32 v133, v9, v193, -v194
	v_cvt_i32_f32_e32 v16, v132
	v_cvt_i32_f32_e32 v17, v133
	v_cmp_ge_f32_e32 vcc, v132, v240
	v_cmp_ge_f32_e64 s[8:9], v133, v240
	v_min_i32_e32 v16, 0x3ff, v16
	v_min_i32_e32 v17, 0x3ff, v17
	v_lshl_add_u32 v16, v16, 2, s41
	v_lshl_add_u32 v17, v17, 2, s41
	v_cndmask_b32_e32 v16, v241, v16, vcc
	v_cndmask_b32_e64 v17, v241, v17, s[8:9]
	ds_add_u32 v16, v206
	ds_add_u32 v17, v206
	s_waitcnt lgkmcnt(6)
	v_fma_f32 v134, v10, v193, -v194
	v_fma_f32 v135, v11, v193, -v194
	v_cvt_i32_f32_e32 v18, v134
	v_cvt_i32_f32_e32 v19, v135
	v_cmp_ge_f32_e32 vcc, v134, v240
	v_cmp_ge_f32_e64 s[8:9], v135, v240
	v_min_i32_e32 v18, 0x3ff, v18
	v_min_i32_e32 v19, 0x3ff, v19
	v_lshl_add_u32 v18, v18, 2, s41
	v_lshl_add_u32 v19, v19, 2, s41
	v_cndmask_b32_e32 v18, v241, v18, vcc
	v_cndmask_b32_e64 v19, v241, v19, s[8:9]
	ds_add_u32 v18, v206
	ds_add_u32 v19, v206
	s_waitcnt lgkmcnt(6)
	v_fma_f32 v136, v12, v193, -v194
	v_fma_f32 v137, v13, v193, -v194
	v_cvt_i32_f32_e32 v20, v136
	v_cvt_i32_f32_e32 v21, v137
	v_cmp_ge_f32_e32 vcc, v136, v240
	v_cmp_ge_f32_e64 s[8:9], v137, v240
	v_min_i32_e32 v20, 0x3ff, v20
	v_min_i32_e32 v21, 0x3ff, v21
	v_lshl_add_u32 v20, v20, 2, s41
	v_lshl_add_u32 v21, v21, 2, s41
	v_cndmask_b32_e32 v20, v241, v20, vcc
	v_cndmask_b32_e64 v21, v241, v21, s[8:9]
	ds_add_u32 v20, v206
	ds_add_u32 v21, v206
	s_waitcnt lgkmcnt(6)
	v_fma_f32 v138, v14, v193, -v194
	v_fma_f32 v139, v15, v193, -v194
	v_cvt_i32_f32_e32 v22, v138
	v_cvt_i32_f32_e32 v23, v139
	v_cmp_ge_f32_e32 vcc, v138, v240
	v_cmp_ge_f32_e64 s[8:9], v139, v240
	v_min_i32_e32 v22, 0x3ff, v22
	v_min_i32_e32 v23, 0x3ff, v23
	v_lshl_add_u32 v22, v22, 2, s41
	v_lshl_add_u32 v23, v23, 2, s41
	v_cndmask_b32_e32 v22, v241, v22, vcc
	v_cndmask_b32_e64 v23, v241, v23, s[8:9]
	ds_add_u32 v22, v206
	ds_add_u32 v23, v206
.Lsel_B_3:
	s_cmp_le_u32 s40, 0xc00
	s_cbranch_scc1 .Lsel_B_done
	s_cmp_lt_u32 s40, 0x1000
	s_cbranch_scc1 .Lsel_B_3_part
	ds_read_b32 v8, v181 offset:12288
	ds_read_b32 v9, v181 offset:12800
	ds_read_b32 v10, v181 offset:13312
	ds_read_b32 v11, v181 offset:13824
	ds_read_b32 v12, v181 offset:14336
	ds_read_b32 v13, v181 offset:14848
	ds_read_b32 v14, v181 offset:15360
	ds_read_b32 v15, v181 offset:15872
	s_waitcnt lgkmcnt(6)
	v_fma_f32 v140, v8, v193, -v194
	v_fma_f32 v141, v9, v193, -v194
	v_cvt_i32_f32_e32 v16, v140
	v_cvt_i32_f32_e32 v17, v141
	v_cmp_ge_f32_e32 vcc, v140, v240
	v_cmp_ge_f32_e64 s[8:9], v141, v240
	v_min_i32_e32 v16, 0x3ff, v16
	v_min_i32_e32 v17, 0x3ff, v17
	v_lshl_add_u32 v16, v16, 2, s41
	v_lshl_add_u32 v17, v17, 2, s41
	v_cndmask_b32_e32 v16, v241, v16, vcc
	v_cndmask_b32_e64 v17, v241, v17, s[8:9]
	ds_add_u32 v16, v206
	ds_add_u32 v17, v206
	s_waitcnt lgkmcnt(6)
	v_fma_f32 v142, v10, v193, -v194
	v_fma_f32 v143, v11, v193, -v194
	v_cvt_i32_f32_e32 v18, v142
	v_cvt_i32_f32_e32 v19, v143
	v_cmp_ge_f32_e32 vcc, v142, v240
	v_cmp_ge_f32_e64 s[8:9], v143, v240
	v_min_i32_e32 v18, 0x3ff, v18
	v_min_i32_e32 v19, 0x3ff, v19
	v_lshl_add_u32 v18, v18, 2, s41
	v_lshl_add_u32 v19, v19, 2, s41
	v_cndmask_b32_e32 v18, v241, v18, vcc
	v_cndmask_b32_e64 v19, v241, v19, s[8:9]
	ds_add_u32 v18, v206
	ds_add_u32 v19, v206
	s_waitcnt lgkmcnt(6)
	v_fma_f32 v144, v12, v193, -v194
	v_fma_f32 v145, v13, v193, -v194
	v_cvt_i32_f32_e32 v20, v144
	v_cvt_i32_f32_e32 v21, v145
	v_cmp_ge_f32_e32 vcc, v144, v240
	v_cmp_ge_f32_e64 s[8:9], v145, v240
	v_min_i32_e32 v20, 0x3ff, v20
	v_min_i32_e32 v21, 0x3ff, v21
	v_lshl_add_u32 v20, v20, 2, s41
	v_lshl_add_u32 v21, v21, 2, s41
	v_cndmask_b32_e32 v20, v241, v20, vcc
	v_cndmask_b32_e64 v21, v241, v21, s[8:9]
	ds_add_u32 v20, v206
	ds_add_u32 v21, v206
	s_waitcnt lgkmcnt(6)
	v_fma_f32 v146, v14, v193, -v194
	v_fma_f32 v147, v15, v193, -v194
	v_cvt_i32_f32_e32 v22, v146
	v_cvt_i32_f32_e32 v23, v147
	v_cmp_ge_f32_e32 vcc, v146, v240
	v_cmp_ge_f32_e64 s[8:9], v147, v240
	v_min_i32_e32 v22, 0x3ff, v22
	v_min_i32_e32 v23, 0x3ff, v23
	v_lshl_add_u32 v22, v22, 2, s41
	v_lshl_add_u32 v23, v23, 2, s41
	v_cndmask_b32_e32 v22, v241, v22, vcc
	v_cndmask_b32_e64 v23, v241, v23, s[8:9]
	ds_add_u32 v22, v206
	ds_add_u32 v23, v206
; DI void selectA_item(const Params& p, int item, int next_item, char* lds, bf16x8 (&qf)[4], float (&wq)[16]) {
;     ...
; #pragma unroll
;     for (int i = 0; i < 64; ++i) { const int idx = gt + 128 * i; const float v = (idx < n) ? scq[idx] : lo; const float u = (v - lo) * scale; uu[i] = u;
;       if (big && idx < n) { int bb = (int)u; bb = bb > 1023 ? 1023 : bb; atomicAdd(&histq[bb], 1); } }
.Lsel_B_4:
	s_cmp_le_u32 s40, 0x1000
	s_cbranch_scc1 .Lsel_B_done
	s_cmp_lt_u32 s40, 0x1400
	s_cbranch_scc1 .Lsel_B_4_part
	ds_read_b32 v8, v181 offset:16384
	ds_read_b32 v9, v181 offset:16896
	ds_read_b32 v10, v181 offset:17408
	ds_read_b32 v11, v181 offset:17920
	ds_read_b32 v12, v181 offset:18432
	ds_read_b32 v13, v181 offset:18944
	ds_read_b32 v14, v181 offset:19456
	ds_read_b32 v15, v181 offset:19968
	s_waitcnt lgkmcnt(6)
	v_fma_f32 v148, v8, v193, -v194
	v_fma_f32 v149, v9, v193, -v194
	v_cvt_i32_f32_e32 v16, v148
	v_cvt_i32_f32_e32 v17, v149
	v_cmp_ge_f32_e32 vcc, v148, v240
	v_cmp_ge_f32_e64 s[8:9], v149, v240
	v_min_i32_e32 v16, 0x3ff, v16
	v_min_i32_e32 v17, 0x3ff, v17
	v_lshl_add_u32 v16, v16, 2, s41
	v_lshl_add_u32 v17, v17, 2, s41
	v_cndmask_b32_e32 v16, v241, v16, vcc
	v_cndmask_b32_e64 v17, v241, v17, s[8:9]
	ds_add_u32 v16, v206
	ds_add_u32 v17, v206
	s_waitcnt lgkmcnt(6)
	v_fma_f32 v150, v10, v193, -v194
	v_fma_f32 v151, v11, v193, -v194
	v_cvt_i32_f32_e32 v18, v150
	v_cvt_i32_f32_e32 v19, v151
	v_cmp_ge_f32_e32 vcc, v150, v240
	v_cmp_ge_f32_e64 s[8:9], v151, v240
	v_min_i32_e32 v18, 0x3ff, v18
	v_min_i32_e32 v19, 0x3ff, v19
	v_lshl_add_u32 v18, v18, 2, s41
	v_lshl_add_u32 v19, v19, 2, s41
	v_cndmask_b32_e32 v18, v241, v18, vcc
	v_cndmask_b32_e64 v19, v241, v19, s[8:9]
	ds_add_u32 v18, v206
	ds_add_u32 v19, v206
	s_waitcnt lgkmcnt(6)
	v_fma_f32 v152, v12, v193, -v194
	v_fma_f32 v153, v13, v193, -v194
	v_cvt_i32_f32_e32 v20, v152
	v_cvt_i32_f32_e32 v21, v153
	v_cmp_ge_f32_e32 vcc, v152, v240
	v_cmp_ge_f32_e64 s[8:9], v153, v240
	v_min_i32_e32 v20, 0x3ff, v20
	v_min_i32_e32 v21, 0x3ff, v21
	v_lshl_add_u32 v20, v20, 2, s41
	v_lshl_add_u32 v21, v21, 2, s41
	v_cndmask_b32_e32 v20, v241, v20, vcc
	v_cndmask_b32_e64 v21, v241, v21, s[8:9]
	ds_add_u32 v20, v206
	ds_add_u32 v21, v206
	s_waitcnt lgkmcnt(6)
	v_fma_f32 v154, v14, v193, -v194
	v_fma_f32 v155, v15, v193, -v194
	v_cvt_i32_f32_e32 v22, v154
	v_cvt_i32_f32_e32 v23, v155
	v_cmp_ge_f32_e32 vcc, v154, v240
	v_cmp_ge_f32_e64 s[8:9], v155, v240
	v_min_i32_e32 v22, 0x3ff, v22
	v_min_i32_e32 v23, 0x3ff, v23
	v_lshl_add_u32 v22, v22, 2, s41
	v_lshl_add_u32 v23, v23, 2, s41
	v_cndmask_b32_e32 v22, v241, v22, vcc
	v_cndmask_b32_e64 v23, v241, v23, s[8:9]
	ds_add_u32 v22, v206
	ds_add_u32 v23, v206
.Lsel_B_5:
	s_cmp_le_u32 s40, 0x1400
	s_cbranch_scc1 .Lsel_B_done
	s_cmp_lt_u32 s40, 0x1800
	s_cbranch_scc1 .Lsel_B_5_part
	ds_read_b32 v8, v181 offset:20480
	ds_read_b32 v9, v181 offset:20992
	ds_read_b32 v10, v181 offset:21504
	ds_read_b32 v11, v181 offset:22016
	ds_read_b32 v12, v181 offset:22528
	ds_read_b32 v13, v181 offset:23040
	ds_read_b32 v14, v181 offset:23552
	ds_read_b32 v15, v181 offset:24064
	s_waitcnt lgkmcnt(6)
	v_fma_f32 v156, v8, v193, -v194
	v_fma_f32 v157, v9, v193, -v194
	v_cvt_i32_f32_e32 v16, v156
	v_cvt_i32_f32_e32 v17, v157
	v_cmp_ge_f32_e32 vcc, v156, v240
	v_cmp_ge_f32_e64 s[8:9], v157, v240
	v_min_i32_e32 v16, 0x3ff, v16
	v_min_i32_e32 v17, 0x3ff, v17
	v_lshl_add_u32 v16, v16, 2, s41
	v_lshl_add_u32 v17, v17, 2, s41
	v_cndmask_b32_e32 v16, v241, v16, vcc
	v_cndmask_b32_e64 v17, v241, v17, s[8:9]
	ds_add_u32 v16, v206
	ds_add_u32 v17, v206
	s_waitcnt lgkmcnt(6)
	v_fma_f32 v158, v10, v193, -v194
	v_fma_f32 v159, v11, v193, -v194
	v_cvt_i32_f32_e32 v18, v158
	v_cvt_i32_f32_e32 v19, v159
	v_cmp_ge_f32_e32 vcc, v158, v240
	v_cmp_ge_f32_e64 s[8:9], v159, v240
	v_min_i32_e32 v18, 0x3ff, v18
	v_min_i32_e32 v19, 0x3ff, v19
	v_lshl_add_u32 v18, v18, 2, s41
	v_lshl_add_u32 v19, v19, 2, s41
	v_cndmask_b32_e32 v18, v241, v18, vcc
	v_cndmask_b32_e64 v19, v241, v19, s[8:9]
	ds_add_u32 v18, v206
	ds_add_u32 v19, v206
	s_waitcnt lgkmcnt(6)
	v_fma_f32 v160, v12, v193, -v194
	v_fma_f32 v161, v13, v193, -v194
	v_cvt_i32_f32_e32 v20, v160
	v_cvt_i32_f32_e32 v21, v161
	v_cmp_ge_f32_e32 vcc, v160, v240
	v_cmp_ge_f32_e64 s[8:9], v161, v240
	v_min_i32_e32 v20, 0x3ff, v20
	v_min_i32_e32 v21, 0x3ff, v21
	v_lshl_add_u32 v20, v20, 2, s41
	v_lshl_add_u32 v21, v21, 2, s41
	v_cndmask_b32_e32 v20, v241, v20, vcc
	v_cndmask_b32_e64 v21, v241, v21, s[8:9]
	ds_add_u32 v20, v206
	ds_add_u32 v21, v206
	s_waitcnt lgkmcnt(6)
	v_fma_f32 v162, v14, v193, -v194
	v_fma_f32 v163, v15, v193, -v194
	v_cvt_i32_f32_e32 v22, v162
	v_cvt_i32_f32_e32 v23, v163
	v_cmp_ge_f32_e32 vcc, v162, v240
	v_cmp_ge_f32_e64 s[8:9], v163, v240
	v_min_i32_e32 v22, 0x3ff, v22
	v_min_i32_e32 v23, 0x3ff, v23
	v_lshl_add_u32 v22, v22, 2, s41
	v_lshl_add_u32 v23, v23, 2, s41
	v_cndmask_b32_e32 v22, v241, v22, vcc
	v_cndmask_b32_e64 v23, v241, v23, s[8:9]
	ds_add_u32 v22, v206
	ds_add_u32 v23, v206
; DI void selectA_item(const Params& p, int item, int next_item, char* lds, bf16x8 (&qf)[4], float (&wq)[16]) {
;     ...
; #pragma unroll
;     for (int i = 0; i < 64; ++i) { const int idx = gt + 128 * i; const float v = (idx < n) ? scq[idx] : lo; const float u = (v - lo) * scale; uu[i] = u;
;       if (big && idx < n) { int bb = (int)u; bb = bb > 1023 ? 1023 : bb; atomicAdd(&histq[bb], 1); } }
.Lsel_B_6:
	s_cmp_le_u32 s40, 0x1800
	s_cbranch_scc1 .Lsel_B_done
	s_cmp_lt_u32 s40, 0x1c00
	s_cbranch_scc1 .Lsel_B_6_part
	ds_read_b32 v8, v181 offset:24576
	ds_read_b32 v9, v181 offset:25088
	ds_read_b32 v10, v181 offset:25600
	ds_read_b32 v11, v181 offset:26112
	ds_read_b32 v12, v181 offset:26624
	ds_read_b32 v13, v181 offset:27136
	ds_read_b32 v14, v181 offset:27648
	ds_read_b32 v15, v181 offset:28160
	s_waitcnt lgkmcnt(6)
	v_fma_f32 v164, v8, v193, -v194
	v_fma_f32 v165, v9, v193, -v194
	v_cvt_i32_f32_e32 v16, v164
	v_cvt_i32_f32_e32 v17, v165
	v_cmp_ge_f32_e32 vcc, v164, v240
	v_cmp_ge_f32_e64 s[8:9], v165, v240
	v_min_i32_e32 v16, 0x3ff, v16
	v_min_i32_e32 v17, 0x3ff, v17
	v_lshl_add_u32 v16, v16, 2, s41
	v_lshl_add_u32 v17, v17, 2, s41
	v_cndmask_b32_e32 v16, v241, v16, vcc
	v_cndmask_b32_e64 v17, v241, v17, s[8:9]
	ds_add_u32 v16, v206
	ds_add_u32 v17, v206
	s_waitcnt lgkmcnt(6)
	v_fma_f32 v166, v10, v193, -v194
	v_fma_f32 v167, v11, v193, -v194
	v_cvt_i32_f32_e32 v18, v166
	v_cvt_i32_f32_e32 v19, v167
	v_cmp_ge_f32_e32 vcc, v166, v240
	v_cmp_ge_f32_e64 s[8:9], v167, v240
	v_min_i32_e32 v18, 0x3ff, v18
	v_min_i32_e32 v19, 0x3ff, v19
	v_lshl_add_u32 v18, v18, 2, s41
	v_lshl_add_u32 v19, v19, 2, s41
	v_cndmask_b32_e32 v18, v241, v18, vcc
	v_cndmask_b32_e64 v19, v241, v19, s[8:9]
	ds_add_u32 v18, v206
	ds_add_u32 v19, v206
	s_waitcnt lgkmcnt(6)
	v_fma_f32 v168, v12, v193, -v194
	v_fma_f32 v169, v13, v193, -v194
	v_cvt_i32_f32_e32 v20, v168
	v_cvt_i32_f32_e32 v21, v169
	v_cmp_ge_f32_e32 vcc, v168, v240
	v_cmp_ge_f32_e64 s[8:9], v169, v240
	v_min_i32_e32 v20, 0x3ff, v20
	v_min_i32_e32 v21, 0x3ff, v21
	v_lshl_add_u32 v20, v20, 2, s41
	v_lshl_add_u32 v21, v21, 2, s41
	v_cndmask_b32_e32 v20, v241, v20, vcc
	v_cndmask_b32_e64 v21, v241, v21, s[8:9]
	ds_add_u32 v20, v206
	ds_add_u32 v21, v206
	s_waitcnt lgkmcnt(6)
	v_fma_f32 v170, v14, v193, -v194
	v_fma_f32 v171, v15, v193, -v194
	v_cvt_i32_f32_e32 v22, v170
	v_cvt_i32_f32_e32 v23, v171
	v_cmp_ge_f32_e32 vcc, v170, v240
	v_cmp_ge_f32_e64 s[8:9], v171, v240
	v_min_i32_e32 v22, 0x3ff, v22
	v_min_i32_e32 v23, 0x3ff, v23
	v_lshl_add_u32 v22, v22, 2, s41
	v_lshl_add_u32 v23, v23, 2, s41
	v_cndmask_b32_e32 v22, v241, v22, vcc
	v_cndmask_b32_e64 v23, v241, v23, s[8:9]
	ds_add_u32 v22, v206
	ds_add_u32 v23, v206
.Lsel_B_7:
	s_cmp_le_u32 s40, 0x1c00
	s_cbranch_scc1 .Lsel_B_done
	s_cmp_lt_u32 s40, 0x2000
	s_cbranch_scc1 .Lsel_B_7_part
	ds_read_b32 v8, v181 offset:28672
	ds_read_b32 v9, v181 offset:29184
	ds_read_b32 v10, v181 offset:29696
	ds_read_b32 v11, v181 offset:30208
	ds_read_b32 v12, v181 offset:30720
	ds_read_b32 v13, v181 offset:31232
	ds_read_b32 v14, v181 offset:31744
	ds_read_b32 v15, v181 offset:32256
	s_waitcnt lgkmcnt(6)
	v_fma_f32 v172, v8, v193, -v194
	v_fma_f32 v173, v9, v193, -v194
	v_cvt_i32_f32_e32 v16, v172
	v_cvt_i32_f32_e32 v17, v173
	v_cmp_ge_f32_e32 vcc, v172, v240
	v_cmp_ge_f32_e64 s[8:9], v173, v240
	v_min_i32_e32 v16, 0x3ff, v16
	v_min_i32_e32 v17, 0x3ff, v17
	v_lshl_add_u32 v16, v16, 2, s41
	v_lshl_add_u32 v17, v17, 2, s41
	v_cndmask_b32_e32 v16, v241, v16, vcc
	v_cndmask_b32_e64 v17, v241, v17, s[8:9]
	ds_add_u32 v16, v206
	ds_add_u32 v17, v206
	s_waitcnt lgkmcnt(6)
	v_fma_f32 v174, v10, v193, -v194
	v_fma_f32 v175, v11, v193, -v194
	v_cvt_i32_f32_e32 v18, v174
	v_cvt_i32_f32_e32 v19, v175
	v_cmp_ge_f32_e32 vcc, v174, v240
	v_cmp_ge_f32_e64 s[8:9], v175, v240
	v_min_i32_e32 v18, 0x3ff, v18
	v_min_i32_e32 v19, 0x3ff, v19
	v_lshl_add_u32 v18, v18, 2, s41
	v_lshl_add_u32 v19, v19, 2, s41
	v_cndmask_b32_e32 v18, v241, v18, vcc
	v_cndmask_b32_e64 v19, v241, v19, s[8:9]
	ds_add_u32 v18, v206
	ds_add_u32 v19, v206
	s_waitcnt lgkmcnt(6)
	v_fma_f32 v176, v12, v193, -v194
	v_fma_f32 v177, v13, v193, -v194
	v_cvt_i32_f32_e32 v20, v176
	v_cvt_i32_f32_e32 v21, v177
	v_cmp_ge_f32_e32 vcc, v176, v240
	v_cmp_ge_f32_e64 s[8:9], v177, v240
	v_min_i32_e32 v20, 0x3ff, v20
	v_min_i32_e32 v21, 0x3ff, v21
	v_lshl_add_u32 v20, v20, 2, s41
	v_lshl_add_u32 v21, v21, 2, s41
	v_cndmask_b32_e32 v20, v241, v20, vcc
	v_cndmask_b32_e64 v21, v241, v21, s[8:9]
	ds_add_u32 v20, v206
	ds_add_u32 v21, v206
	s_waitcnt lgkmcnt(6)
	v_fma_f32 v178, v14, v193, -v194
	v_fma_f32 v179, v15, v193, -v194
	v_cvt_i32_f32_e32 v22, v178
	v_cvt_i32_f32_e32 v23, v179
	v_cmp_ge_f32_e32 vcc, v178, v240
	v_cmp_ge_f32_e64 s[8:9], v179, v240
	v_min_i32_e32 v22, 0x3ff, v22
	v_min_i32_e32 v23, 0x3ff, v23
	v_lshl_add_u32 v22, v22, 2, s41
	v_lshl_add_u32 v23, v23, 2, s41
	v_cndmask_b32_e32 v22, v241, v22, vcc
	v_cndmask_b32_e64 v23, v241, v23, s[8:9]
	ds_add_u32 v22, v206
	ds_add_u32 v23, v206
	s_branch .Lsel_B_done
; DI void selectA_item(const Params& p, int item, int next_item, char* lds, bf16x8 (&qf)[4], float (&wq)[16]) {
;     ...
; #pragma unroll
;     for (int i = 0; i < 64; ++i) { const int idx = gt + 128 * i; const float v = (idx < n) ? scq[idx] : lo; const float u = (v - lo) * scale; uu[i] = u;
;       if (big && idx < n) { int bb = (int)u; bb = bb > 1023 ? 1023 : bb; atomicAdd(&histq[bb], 1); } }
.Lsel_B_0_part:
	s_mov_b32 s2, s40
	ds_read_b32 v8, v181 offset:0
	ds_read_b32 v9, v181 offset:512
	ds_read_b32 v10, v181 offset:1024
	ds_read_b32 v11, v181 offset:1536
	ds_read_b32 v12, v181 offset:2048
	ds_read_b32 v13, v181 offset:2560
	ds_read_b32 v14, v181 offset:3072
	ds_read_b32 v15, v181 offset:3584
	v_cmp_gt_i32_e64 s[66:67], s2, v180
	s_sub_i32 s3, s2, 0x80
	v_cmp_gt_i32_e64 s[68:69], s3, v180
	s_sub_i32 s3, s2, 0x100
	v_cmp_gt_i32_e64 s[70:71], s3, v180
	s_sub_i32 s3, s2, 0x180
	v_cmp_gt_i32_e64 s[72:73], s3, v180
	s_sub_i32 s3, s2, 0x200
	v_cmp_gt_i32_e64 s[74:75], s3, v180
	s_sub_i32 s3, s2, 0x280
	v_cmp_gt_i32_e64 s[76:77], s3, v180
	s_sub_i32 s3, s2, 0x300
	v_cmp_gt_i32_e64 s[78:79], s3, v180
	s_sub_i32 s3, s2, 0x380
	v_cmp_gt_i32_e64 s[80:81], s3, v180
	s_waitcnt lgkmcnt(7)
	v_fma_f32 v8, v8, v193, -v194
	v_cndmask_b32_e64 v116, -1.0, v8, s[66:67]
	v_cvt_i32_f32_e32 v16, v116
	v_cmp_ge_f32_e32 vcc, v116, v240
	v_min_i32_e32 v16, 0x3ff, v16
	v_lshl_add_u32 v16, v16, 2, s41
	v_cndmask_b32_e64 v16, v205, v16, s[66:67]
	v_cndmask_b32_e32 v16, v241, v16, vcc
	ds_add_u32 v16, v206
	s_waitcnt lgkmcnt(7)
	v_fma_f32 v9, v9, v193, -v194
	v_cndmask_b32_e64 v117, -1.0, v9, s[68:69]
	v_cvt_i32_f32_e32 v17, v117
	v_cmp_ge_f32_e32 vcc, v117, v240
	v_min_i32_e32 v17, 0x3ff, v17
	v_lshl_add_u32 v17, v17, 2, s41
	v_cndmask_b32_e64 v17, v205, v17, s[68:69]
	v_cndmask_b32_e32 v17, v241, v17, vcc
	ds_add_u32 v17, v206
	s_waitcnt lgkmcnt(7)
	v_fma_f32 v10, v10, v193, -v194
	v_cndmask_b32_e64 v118, -1.0, v10, s[70:71]
	v_cvt_i32_f32_e32 v18, v118
	v_cmp_ge_f32_e32 vcc, v118, v240
	v_min_i32_e32 v18, 0x3ff, v18
	v_lshl_add_u32 v18, v18, 2, s41
	v_cndmask_b32_e64 v18, v205, v18, s[70:71]
	v_cndmask_b32_e32 v18, v241, v18, vcc
	ds_add_u32 v18, v206
	s_waitcnt lgkmcnt(7)
	v_fma_f32 v11, v11, v193, -v194
	v_cndmask_b32_e64 v119, -1.0, v11, s[72:73]
	v_cvt_i32_f32_e32 v19, v119
	v_cmp_ge_f32_e32 vcc, v119, v240
	v_min_i32_e32 v19, 0x3ff, v19
	v_lshl_add_u32 v19, v19, 2, s41
	v_cndmask_b32_e64 v19, v205, v19, s[72:73]
	v_cndmask_b32_e32 v19, v241, v19, vcc
	ds_add_u32 v19, v206
	s_waitcnt lgkmcnt(7)
	v_fma_f32 v12, v12, v193, -v194
	v_cndmask_b32_e64 v120, -1.0, v12, s[74:75]
	v_cvt_i32_f32_e32 v20, v120
	v_cmp_ge_f32_e32 vcc, v120, v240
	v_min_i32_e32 v20, 0x3ff, v20
	v_lshl_add_u32 v20, v20, 2, s41
	v_cndmask_b32_e64 v20, v205, v20, s[74:75]
	v_cndmask_b32_e32 v20, v241, v20, vcc
	ds_add_u32 v20, v206
	s_waitcnt lgkmcnt(7)
	v_fma_f32 v13, v13, v193, -v194
	v_cndmask_b32_e64 v121, -1.0, v13, s[76:77]
	v_cvt_i32_f32_e32 v21, v121
	v_cmp_ge_f32_e32 vcc, v121, v240
	v_min_i32_e32 v21, 0x3ff, v21
	v_lshl_add_u32 v21, v21, 2, s41
	v_cndmask_b32_e64 v21, v205, v21, s[76:77]
	v_cndmask_b32_e32 v21, v241, v21, vcc
	ds_add_u32 v21, v206
	s_waitcnt lgkmcnt(7)
	v_fma_f32 v14, v14, v193, -v194
	v_cndmask_b32_e64 v122, -1.0, v14, s[78:79]
	v_cvt_i32_f32_e32 v22, v122
	v_cmp_ge_f32_e32 vcc, v122, v240
	v_min_i32_e32 v22, 0x3ff, v22
	v_lshl_add_u32 v22, v22, 2, s41
	v_cndmask_b32_e64 v22, v205, v22, s[78:79]
	v_cndmask_b32_e32 v22, v241, v22, vcc
	ds_add_u32 v22, v206
	s_waitcnt lgkmcnt(7)
	v_fma_f32 v15, v15, v193, -v194
	v_cndmask_b32_e64 v123, -1.0, v15, s[80:81]
	v_cvt_i32_f32_e32 v23, v123
	v_cmp_ge_f32_e32 vcc, v123, v240
	v_min_i32_e32 v23, 0x3ff, v23
	v_lshl_add_u32 v23, v23, 2, s41
	v_cndmask_b32_e64 v23, v205, v23, s[80:81]
	v_cndmask_b32_e32 v23, v241, v23, vcc
	ds_add_u32 v23, v206
	s_branch .Lsel_B_done
.Lsel_B_1_part:
	s_sub_i32 s2, s40, 0x400
	ds_read_b32 v8, v181 offset:4096
	ds_read_b32 v9, v181 offset:4608
	ds_read_b32 v10, v181 offset:5120
	ds_read_b32 v11, v181 offset:5632
	ds_read_b32 v12, v181 offset:6144
	ds_read_b32 v13, v181 offset:6656
	ds_read_b32 v14, v181 offset:7168
	ds_read_b32 v15, v181 offset:7680
	v_cmp_gt_i32_e64 s[66:67], s2, v180
	s_sub_i32 s3, s2, 0x80
	v_cmp_gt_i32_e64 s[68:69], s3, v180
	s_sub_i32 s3, s2, 0x100
	v_cmp_gt_i32_e64 s[70:71], s3, v180
	s_sub_i32 s3, s2, 0x180
	v_cmp_gt_i32_e64 s[72:73], s3, v180
	s_sub_i32 s3, s2, 0x200
	v_cmp_gt_i32_e64 s[74:75], s3, v180
	s_sub_i32 s3, s2, 0x280
	v_cmp_gt_i32_e64 s[76:77], s3, v180
	s_sub_i32 s3, s2, 0x300
	v_cmp_gt_i32_e64 s[78:79], s3, v180
	s_sub_i32 s3, s2, 0x380
	v_cmp_gt_i32_e64 s[80:81], s3, v180
	s_waitcnt lgkmcnt(7)
	v_fma_f32 v8, v8, v193, -v194
	v_cndmask_b32_e64 v124, -1.0, v8, s[66:67]
	v_cvt_i32_f32_e32 v16, v124
	v_cmp_ge_f32_e32 vcc, v124, v240
	v_min_i32_e32 v16, 0x3ff, v16
	v_lshl_add_u32 v16, v16, 2, s41
	v_cndmask_b32_e64 v16, v205, v16, s[66:67]
	v_cndmask_b32_e32 v16, v241, v16, vcc
	ds_add_u32 v16, v206
	s_waitcnt lgkmcnt(7)
	v_fma_f32 v9, v9, v193, -v194
	v_cndmask_b32_e64 v125, -1.0, v9, s[68:69]
	v_cvt_i32_f32_e32 v17, v125
	v_cmp_ge_f32_e32 vcc, v125, v240
	v_min_i32_e32 v17, 0x3ff, v17
	v_lshl_add_u32 v17, v17, 2, s41
	v_cndmask_b32_e64 v17, v205, v17, s[68:69]
	v_cndmask_b32_e32 v17, v241, v17, vcc
	ds_add_u32 v17, v206
	s_waitcnt lgkmcnt(7)
	v_fma_f32 v10, v10, v193, -v194
	v_cndmask_b32_e64 v126, -1.0, v10, s[70:71]
	v_cvt_i32_f32_e32 v18, v126
	v_cmp_ge_f32_e32 vcc, v126, v240
	v_min_i32_e32 v18, 0x3ff, v18
	v_lshl_add_u32 v18, v18, 2, s41
	v_cndmask_b32_e64 v18, v205, v18, s[70:71]
	v_cndmask_b32_e32 v18, v241, v18, vcc
	ds_add_u32 v18, v206
	s_waitcnt lgkmcnt(7)
	v_fma_f32 v11, v11, v193, -v194
	v_cndmask_b32_e64 v127, -1.0, v11, s[72:73]
	v_cvt_i32_f32_e32 v19, v127
	v_cmp_ge_f32_e32 vcc, v127, v240
	v_min_i32_e32 v19, 0x3ff, v19
	v_lshl_add_u32 v19, v19, 2, s41
	v_cndmask_b32_e64 v19, v205, v19, s[72:73]
	v_cndmask_b32_e32 v19, v241, v19, vcc
	ds_add_u32 v19, v206
	s_waitcnt lgkmcnt(7)
	v_fma_f32 v12, v12, v193, -v194
	v_cndmask_b32_e64 v128, -1.0, v12, s[74:75]
	v_cvt_i32_f32_e32 v20, v128
	v_cmp_ge_f32_e32 vcc, v128, v240
	v_min_i32_e32 v20, 0x3ff, v20
	v_lshl_add_u32 v20, v20, 2, s41
	v_cndmask_b32_e64 v20, v205, v20, s[74:75]
	v_cndmask_b32_e32 v20, v241, v20, vcc
	ds_add_u32 v20, v206
	s_waitcnt lgkmcnt(7)
	v_fma_f32 v13, v13, v193, -v194
	v_cndmask_b32_e64 v129, -1.0, v13, s[76:77]
	v_cvt_i32_f32_e32 v21, v129
	v_cmp_ge_f32_e32 vcc, v129, v240
	v_min_i32_e32 v21, 0x3ff, v21
	v_lshl_add_u32 v21, v21, 2, s41
	v_cndmask_b32_e64 v21, v205, v21, s[76:77]
	v_cndmask_b32_e32 v21, v241, v21, vcc
	ds_add_u32 v21, v206
	s_waitcnt lgkmcnt(7)
	v_fma_f32 v14, v14, v193, -v194
	v_cndmask_b32_e64 v130, -1.0, v14, s[78:79]
	v_cvt_i32_f32_e32 v22, v130
	v_cmp_ge_f32_e32 vcc, v130, v240
	v_min_i32_e32 v22, 0x3ff, v22
	v_lshl_add_u32 v22, v22, 2, s41
	v_cndmask_b32_e64 v22, v205, v22, s[78:79]
	v_cndmask_b32_e32 v22, v241, v22, vcc
	ds_add_u32 v22, v206
	s_waitcnt lgkmcnt(7)
	v_fma_f32 v15, v15, v193, -v194
	v_cndmask_b32_e64 v131, -1.0, v15, s[80:81]
	v_cvt_i32_f32_e32 v23, v131
	v_cmp_ge_f32_e32 vcc, v131, v240
	v_min_i32_e32 v23, 0x3ff, v23
	v_lshl_add_u32 v23, v23, 2, s41
	v_cndmask_b32_e64 v23, v205, v23, s[80:81]
	v_cndmask_b32_e32 v23, v241, v23, vcc
	ds_add_u32 v23, v206
	s_branch .Lsel_B_done
; DI void selectA_item(const Params& p, int item, int next_item, char* lds, bf16x8 (&qf)[4], float (&wq)[16]) {
;     ...
; #pragma unroll
;     for (int i = 0; i < 64; ++i) { const int idx = gt + 128 * i; const float v = (idx < n) ? scq[idx] : lo; const float u = (v - lo) * scale; uu[i] = u;
;       if (big && idx < n) { int bb = (int)u; bb = bb > 1023 ? 1023 : bb; atomicAdd(&histq[bb], 1); } }
.Lsel_B_2_part:
	s_sub_i32 s2, s40, 0x800
	ds_read_b32 v8, v181 offset:8192
	ds_read_b32 v9, v181 offset:8704
	ds_read_b32 v10, v181 offset:9216
	ds_read_b32 v11, v181 offset:9728
	ds_read_b32 v12, v181 offset:10240
	ds_read_b32 v13, v181 offset:10752
	ds_read_b32 v14, v181 offset:11264
	ds_read_b32 v15, v181 offset:11776
	v_cmp_gt_i32_e64 s[66:67], s2, v180
	s_sub_i32 s3, s2, 0x80
	v_cmp_gt_i32_e64 s[68:69], s3, v180
	s_sub_i32 s3, s2, 0x100
	v_cmp_gt_i32_e64 s[70:71], s3, v180
	s_sub_i32 s3, s2, 0x180
	v_cmp_gt_i32_e64 s[72:73], s3, v180
	s_sub_i32 s3, s2, 0x200
	v_cmp_gt_i32_e64 s[74:75], s3, v180
	s_sub_i32 s3, s2, 0x280
	v_cmp_gt_i32_e64 s[76:77], s3, v180
	s_sub_i32 s3, s2, 0x300
	v_cmp_gt_i32_e64 s[78:79], s3, v180
	s_sub_i32 s3, s2, 0x380
	v_cmp_gt_i32_e64 s[80:81], s3, v180
	s_waitcnt lgkmcnt(7)
	v_fma_f32 v8, v8, v193, -v194
	v_cndmask_b32_e64 v132, -1.0, v8, s[66:67]
	v_cvt_i32_f32_e32 v16, v132
	v_cmp_ge_f32_e32 vcc, v132, v240
	v_min_i32_e32 v16, 0x3ff, v16
	v_lshl_add_u32 v16, v16, 2, s41
	v_cndmask_b32_e64 v16, v205, v16, s[66:67]
	v_cndmask_b32_e32 v16, v241, v16, vcc
	ds_add_u32 v16, v206
	s_waitcnt lgkmcnt(7)
	v_fma_f32 v9, v9, v193, -v194
	v_cndmask_b32_e64 v133, -1.0, v9, s[68:69]
	v_cvt_i32_f32_e32 v17, v133
	v_cmp_ge_f32_e32 vcc, v133, v240
	v_min_i32_e32 v17, 0x3ff, v17
	v_lshl_add_u32 v17, v17, 2, s41
	v_cndmask_b32_e64 v17, v205, v17, s[68:69]
	v_cndmask_b32_e32 v17, v241, v17, vcc
	ds_add_u32 v17, v206
	s_waitcnt lgkmcnt(7)
	v_fma_f32 v10, v10, v193, -v194
	v_cndmask_b32_e64 v134, -1.0, v10, s[70:71]
	v_cvt_i32_f32_e32 v18, v134
	v_cmp_ge_f32_e32 vcc, v134, v240
	v_min_i32_e32 v18, 0x3ff, v18
	v_lshl_add_u32 v18, v18, 2, s41
	v_cndmask_b32_e64 v18, v205, v18, s[70:71]
	v_cndmask_b32_e32 v18, v241, v18, vcc
	ds_add_u32 v18, v206
	s_waitcnt lgkmcnt(7)
	v_fma_f32 v11, v11, v193, -v194
	v_cndmask_b32_e64 v135, -1.0, v11, s[72:73]
	v_cvt_i32_f32_e32 v19, v135
	v_cmp_ge_f32_e32 vcc, v135, v240
	v_min_i32_e32 v19, 0x3ff, v19
	v_lshl_add_u32 v19, v19, 2, s41
	v_cndmask_b32_e64 v19, v205, v19, s[72:73]
	v_cndmask_b32_e32 v19, v241, v19, vcc
	ds_add_u32 v19, v206
	s_waitcnt lgkmcnt(7)
	v_fma_f32 v12, v12, v193, -v194
	v_cndmask_b32_e64 v136, -1.0, v12, s[74:75]
	v_cvt_i32_f32_e32 v20, v136
	v_cmp_ge_f32_e32 vcc, v136, v240
	v_min_i32_e32 v20, 0x3ff, v20
	v_lshl_add_u32 v20, v20, 2, s41
	v_cndmask_b32_e64 v20, v205, v20, s[74:75]
	v_cndmask_b32_e32 v20, v241, v20, vcc
	ds_add_u32 v20, v206
	s_waitcnt lgkmcnt(7)
	v_fma_f32 v13, v13, v193, -v194
	v_cndmask_b32_e64 v137, -1.0, v13, s[76:77]
	v_cvt_i32_f32_e32 v21, v137
	v_cmp_ge_f32_e32 vcc, v137, v240
	v_min_i32_e32 v21, 0x3ff, v21
	v_lshl_add_u32 v21, v21, 2, s41
	v_cndmask_b32_e64 v21, v205, v21, s[76:77]
	v_cndmask_b32_e32 v21, v241, v21, vcc
	ds_add_u32 v21, v206
	s_waitcnt lgkmcnt(7)
	v_fma_f32 v14, v14, v193, -v194
	v_cndmask_b32_e64 v138, -1.0, v14, s[78:79]
	v_cvt_i32_f32_e32 v22, v138
	v_cmp_ge_f32_e32 vcc, v138, v240
	v_min_i32_e32 v22, 0x3ff, v22
	v_lshl_add_u32 v22, v22, 2, s41
	v_cndmask_b32_e64 v22, v205, v22, s[78:79]
	v_cndmask_b32_e32 v22, v241, v22, vcc
	ds_add_u32 v22, v206
	s_waitcnt lgkmcnt(7)
	v_fma_f32 v15, v15, v193, -v194
	v_cndmask_b32_e64 v139, -1.0, v15, s[80:81]
	v_cvt_i32_f32_e32 v23, v139
	v_cmp_ge_f32_e32 vcc, v139, v240
	v_min_i32_e32 v23, 0x3ff, v23
	v_lshl_add_u32 v23, v23, 2, s41
	v_cndmask_b32_e64 v23, v205, v23, s[80:81]
	v_cndmask_b32_e32 v23, v241, v23, vcc
	ds_add_u32 v23, v206
	s_branch .Lsel_B_done
.Lsel_B_3_part:
	s_sub_i32 s2, s40, 0xc00
	ds_read_b32 v8, v181 offset:12288
	ds_read_b32 v9, v181 offset:12800
	ds_read_b32 v10, v181 offset:13312
	ds_read_b32 v11, v181 offset:13824
	ds_read_b32 v12, v181 offset:14336
	ds_read_b32 v13, v181 offset:14848
	ds_read_b32 v14, v181 offset:15360
	ds_read_b32 v15, v181 offset:15872
	v_cmp_gt_i32_e64 s[66:67], s2, v180
	s_sub_i32 s3, s2, 0x80
	v_cmp_gt_i32_e64 s[68:69], s3, v180
	s_sub_i32 s3, s2, 0x100
	v_cmp_gt_i32_e64 s[70:71], s3, v180
	s_sub_i32 s3, s2, 0x180
	v_cmp_gt_i32_e64 s[72:73], s3, v180
	s_sub_i32 s3, s2, 0x200
	v_cmp_gt_i32_e64 s[74:75], s3, v180
	s_sub_i32 s3, s2, 0x280
	v_cmp_gt_i32_e64 s[76:77], s3, v180
	s_sub_i32 s3, s2, 0x300
	v_cmp_gt_i32_e64 s[78:79], s3, v180
	s_sub_i32 s3, s2, 0x380
	v_cmp_gt_i32_e64 s[80:81], s3, v180
	s_waitcnt lgkmcnt(7)
	v_fma_f32 v8, v8, v193, -v194
	v_cndmask_b32_e64 v140, -1.0, v8, s[66:67]
	v_cvt_i32_f32_e32 v16, v140
	v_cmp_ge_f32_e32 vcc, v140, v240
	v_min_i32_e32 v16, 0x3ff, v16
	v_lshl_add_u32 v16, v16, 2, s41
	v_cndmask_b32_e64 v16, v205, v16, s[66:67]
	v_cndmask_b32_e32 v16, v241, v16, vcc
	ds_add_u32 v16, v206
	s_waitcnt lgkmcnt(7)
	v_fma_f32 v9, v9, v193, -v194
	v_cndmask_b32_e64 v141, -1.0, v9, s[68:69]
	v_cvt_i32_f32_e32 v17, v141
	v_cmp_ge_f32_e32 vcc, v141, v240
	v_min_i32_e32 v17, 0x3ff, v17
	v_lshl_add_u32 v17, v17, 2, s41
	v_cndmask_b32_e64 v17, v205, v17, s[68:69]
	v_cndmask_b32_e32 v17, v241, v17, vcc
	ds_add_u32 v17, v206
	s_waitcnt lgkmcnt(7)
	v_fma_f32 v10, v10, v193, -v194
	v_cndmask_b32_e64 v142, -1.0, v10, s[70:71]
	v_cvt_i32_f32_e32 v18, v142
	v_cmp_ge_f32_e32 vcc, v142, v240
	v_min_i32_e32 v18, 0x3ff, v18
	v_lshl_add_u32 v18, v18, 2, s41
	v_cndmask_b32_e64 v18, v205, v18, s[70:71]
	v_cndmask_b32_e32 v18, v241, v18, vcc
	ds_add_u32 v18, v206
	s_waitcnt lgkmcnt(7)
	v_fma_f32 v11, v11, v193, -v194
	v_cndmask_b32_e64 v143, -1.0, v11, s[72:73]
	v_cvt_i32_f32_e32 v19, v143
	v_cmp_ge_f32_e32 vcc, v143, v240
	v_min_i32_e32 v19, 0x3ff, v19
	v_lshl_add_u32 v19, v19, 2, s41
	v_cndmask_b32_e64 v19, v205, v19, s[72:73]
	v_cndmask_b32_e32 v19, v241, v19, vcc
	ds_add_u32 v19, v206
	s_waitcnt lgkmcnt(7)
	v_fma_f32 v12, v12, v193, -v194
	v_cndmask_b32_e64 v144, -1.0, v12, s[74:75]
	v_cvt_i32_f32_e32 v20, v144
	v_cmp_ge_f32_e32 vcc, v144, v240
	v_min_i32_e32 v20, 0x3ff, v20
	v_lshl_add_u32 v20, v20, 2, s41
	v_cndmask_b32_e64 v20, v205, v20, s[74:75]
	v_cndmask_b32_e32 v20, v241, v20, vcc
	ds_add_u32 v20, v206
	s_waitcnt lgkmcnt(7)
	v_fma_f32 v13, v13, v193, -v194
	v_cndmask_b32_e64 v145, -1.0, v13, s[76:77]
	v_cvt_i32_f32_e32 v21, v145
	v_cmp_ge_f32_e32 vcc, v145, v240
	v_min_i32_e32 v21, 0x3ff, v21
	v_lshl_add_u32 v21, v21, 2, s41
	v_cndmask_b32_e64 v21, v205, v21, s[76:77]
	v_cndmask_b32_e32 v21, v241, v21, vcc
	ds_add_u32 v21, v206
	s_waitcnt lgkmcnt(7)
	v_fma_f32 v14, v14, v193, -v194
	v_cndmask_b32_e64 v146, -1.0, v14, s[78:79]
	v_cvt_i32_f32_e32 v22, v146
	v_cmp_ge_f32_e32 vcc, v146, v240
	v_min_i32_e32 v22, 0x3ff, v22
	v_lshl_add_u32 v22, v22, 2, s41
	v_cndmask_b32_e64 v22, v205, v22, s[78:79]
	v_cndmask_b32_e32 v22, v241, v22, vcc
	ds_add_u32 v22, v206
	s_waitcnt lgkmcnt(7)
	v_fma_f32 v15, v15, v193, -v194
	v_cndmask_b32_e64 v147, -1.0, v15, s[80:81]
	v_cvt_i32_f32_e32 v23, v147
	v_cmp_ge_f32_e32 vcc, v147, v240
	v_min_i32_e32 v23, 0x3ff, v23
	v_lshl_add_u32 v23, v23, 2, s41
	v_cndmask_b32_e64 v23, v205, v23, s[80:81]
	v_cndmask_b32_e32 v23, v241, v23, vcc
	ds_add_u32 v23, v206
	s_branch .Lsel_B_done
; DI void selectA_item(const Params& p, int item, int next_item, char* lds, bf16x8 (&qf)[4], float (&wq)[16]) {
;     ...
; #pragma unroll
;     for (int i = 0; i < 64; ++i) { const int idx = gt + 128 * i; const float v = (idx < n) ? scq[idx] : lo; const float u = (v - lo) * scale; uu[i] = u;
;       if (big && idx < n) { int bb = (int)u; bb = bb > 1023 ? 1023 : bb; atomicAdd(&histq[bb], 1); } }
.Lsel_B_4_part:
	s_sub_i32 s2, s40, 0x1000
	ds_read_b32 v8, v181 offset:16384
	ds_read_b32 v9, v181 offset:16896
	ds_read_b32 v10, v181 offset:17408
	ds_read_b32 v11, v181 offset:17920
	ds_read_b32 v12, v181 offset:18432
	ds_read_b32 v13, v181 offset:18944
	ds_read_b32 v14, v181 offset:19456
	ds_read_b32 v15, v181 offset:19968
	v_cmp_gt_i32_e64 s[66:67], s2, v180
	s_sub_i32 s3, s2, 0x80
	v_cmp_gt_i32_e64 s[68:69], s3, v180
	s_sub_i32 s3, s2, 0x100
	v_cmp_gt_i32_e64 s[70:71], s3, v180
	s_sub_i32 s3, s2, 0x180
	v_cmp_gt_i32_e64 s[72:73], s3, v180
	s_sub_i32 s3, s2, 0x200
	v_cmp_gt_i32_e64 s[74:75], s3, v180
	s_sub_i32 s3, s2, 0x280
	v_cmp_gt_i32_e64 s[76:77], s3, v180
	s_sub_i32 s3, s2, 0x300
	v_cmp_gt_i32_e64 s[78:79], s3, v180
	s_sub_i32 s3, s2, 0x380
	v_cmp_gt_i32_e64 s[80:81], s3, v180
	s_waitcnt lgkmcnt(7)
	v_fma_f32 v8, v8, v193, -v194
	v_cndmask_b32_e64 v148, -1.0, v8, s[66:67]
	v_cvt_i32_f32_e32 v16, v148
	v_cmp_ge_f32_e32 vcc, v148, v240
	v_min_i32_e32 v16, 0x3ff, v16
	v_lshl_add_u32 v16, v16, 2, s41
	v_cndmask_b32_e64 v16, v205, v16, s[66:67]
	v_cndmask_b32_e32 v16, v241, v16, vcc
	ds_add_u32 v16, v206
	s_waitcnt lgkmcnt(7)
	v_fma_f32 v9, v9, v193, -v194
	v_cndmask_b32_e64 v149, -1.0, v9, s[68:69]
	v_cvt_i32_f32_e32 v17, v149
	v_cmp_ge_f32_e32 vcc, v149, v240
	v_min_i32_e32 v17, 0x3ff, v17
	v_lshl_add_u32 v17, v17, 2, s41
	v_cndmask_b32_e64 v17, v205, v17, s[68:69]
	v_cndmask_b32_e32 v17, v241, v17, vcc
	ds_add_u32 v17, v206
	s_waitcnt lgkmcnt(7)
	v_fma_f32 v10, v10, v193, -v194
	v_cndmask_b32_e64 v150, -1.0, v10, s[70:71]
	v_cvt_i32_f32_e32 v18, v150
	v_cmp_ge_f32_e32 vcc, v150, v240
	v_min_i32_e32 v18, 0x3ff, v18
	v_lshl_add_u32 v18, v18, 2, s41
	v_cndmask_b32_e64 v18, v205, v18, s[70:71]
	v_cndmask_b32_e32 v18, v241, v18, vcc
	ds_add_u32 v18, v206
	s_waitcnt lgkmcnt(7)
	v_fma_f32 v11, v11, v193, -v194
	v_cndmask_b32_e64 v151, -1.0, v11, s[72:73]
	v_cvt_i32_f32_e32 v19, v151
	v_cmp_ge_f32_e32 vcc, v151, v240
	v_min_i32_e32 v19, 0x3ff, v19
	v_lshl_add_u32 v19, v19, 2, s41
	v_cndmask_b32_e64 v19, v205, v19, s[72:73]
	v_cndmask_b32_e32 v19, v241, v19, vcc
	ds_add_u32 v19, v206
	s_waitcnt lgkmcnt(7)
	v_fma_f32 v12, v12, v193, -v194
	v_cndmask_b32_e64 v152, -1.0, v12, s[74:75]
	v_cvt_i32_f32_e32 v20, v152
	v_cmp_ge_f32_e32 vcc, v152, v240
	v_min_i32_e32 v20, 0x3ff, v20
	v_lshl_add_u32 v20, v20, 2, s41
	v_cndmask_b32_e64 v20, v205, v20, s[74:75]
	v_cndmask_b32_e32 v20, v241, v20, vcc
	ds_add_u32 v20, v206
	s_waitcnt lgkmcnt(7)
	v_fma_f32 v13, v13, v193, -v194
	v_cndmask_b32_e64 v153, -1.0, v13, s[76:77]
	v_cvt_i32_f32_e32 v21, v153
	v_cmp_ge_f32_e32 vcc, v153, v240
	v_min_i32_e32 v21, 0x3ff, v21
	v_lshl_add_u32 v21, v21, 2, s41
	v_cndmask_b32_e64 v21, v205, v21, s[76:77]
	v_cndmask_b32_e32 v21, v241, v21, vcc
	ds_add_u32 v21, v206
	s_waitcnt lgkmcnt(7)
	v_fma_f32 v14, v14, v193, -v194
	v_cndmask_b32_e64 v154, -1.0, v14, s[78:79]
	v_cvt_i32_f32_e32 v22, v154
	v_cmp_ge_f32_e32 vcc, v154, v240
	v_min_i32_e32 v22, 0x3ff, v22
	v_lshl_add_u32 v22, v22, 2, s41
	v_cndmask_b32_e64 v22, v205, v22, s[78:79]
	v_cndmask_b32_e32 v22, v241, v22, vcc
	ds_add_u32 v22, v206
	s_waitcnt lgkmcnt(7)
	v_fma_f32 v15, v15, v193, -v194
	v_cndmask_b32_e64 v155, -1.0, v15, s[80:81]
	v_cvt_i32_f32_e32 v23, v155
	v_cmp_ge_f32_e32 vcc, v155, v240
	v_min_i32_e32 v23, 0x3ff, v23
	v_lshl_add_u32 v23, v23, 2, s41
	v_cndmask_b32_e64 v23, v205, v23, s[80:81]
	v_cndmask_b32_e32 v23, v241, v23, vcc
	ds_add_u32 v23, v206
	s_branch .Lsel_B_done
.Lsel_B_5_part:
	s_sub_i32 s2, s40, 0x1400
	ds_read_b32 v8, v181 offset:20480
	ds_read_b32 v9, v181 offset:20992
	ds_read_b32 v10, v181 offset:21504
	ds_read_b32 v11, v181 offset:22016
	ds_read_b32 v12, v181 offset:22528
	ds_read_b32 v13, v181 offset:23040
	ds_read_b32 v14, v181 offset:23552
	ds_read_b32 v15, v181 offset:24064
	v_cmp_gt_i32_e64 s[66:67], s2, v180
	s_sub_i32 s3, s2, 0x80
	v_cmp_gt_i32_e64 s[68:69], s3, v180
	s_sub_i32 s3, s2, 0x100
	v_cmp_gt_i32_e64 s[70:71], s3, v180
	s_sub_i32 s3, s2, 0x180
	v_cmp_gt_i32_e64 s[72:73], s3, v180
	s_sub_i32 s3, s2, 0x200
	v_cmp_gt_i32_e64 s[74:75], s3, v180
	s_sub_i32 s3, s2, 0x280
	v_cmp_gt_i32_e64 s[76:77], s3, v180
	s_sub_i32 s3, s2, 0x300
	v_cmp_gt_i32_e64 s[78:79], s3, v180
	s_sub_i32 s3, s2, 0x380
	v_cmp_gt_i32_e64 s[80:81], s3, v180
	s_waitcnt lgkmcnt(7)
	v_fma_f32 v8, v8, v193, -v194
	v_cndmask_b32_e64 v156, -1.0, v8, s[66:67]
	v_cvt_i32_f32_e32 v16, v156
	v_cmp_ge_f32_e32 vcc, v156, v240
	v_min_i32_e32 v16, 0x3ff, v16
	v_lshl_add_u32 v16, v16, 2, s41
	v_cndmask_b32_e64 v16, v205, v16, s[66:67]
	v_cndmask_b32_e32 v16, v241, v16, vcc
	ds_add_u32 v16, v206
	s_waitcnt lgkmcnt(7)
	v_fma_f32 v9, v9, v193, -v194
	v_cndmask_b32_e64 v157, -1.0, v9, s[68:69]
	v_cvt_i32_f32_e32 v17, v157
	v_cmp_ge_f32_e32 vcc, v157, v240
	v_min_i32_e32 v17, 0x3ff, v17
	v_lshl_add_u32 v17, v17, 2, s41
	v_cndmask_b32_e64 v17, v205, v17, s[68:69]
	v_cndmask_b32_e32 v17, v241, v17, vcc
	ds_add_u32 v17, v206
	s_waitcnt lgkmcnt(7)
	v_fma_f32 v10, v10, v193, -v194
	v_cndmask_b32_e64 v158, -1.0, v10, s[70:71]
	v_cvt_i32_f32_e32 v18, v158
	v_cmp_ge_f32_e32 vcc, v158, v240
	v_min_i32_e32 v18, 0x3ff, v18
	v_lshl_add_u32 v18, v18, 2, s41
	v_cndmask_b32_e64 v18, v205, v18, s[70:71]
	v_cndmask_b32_e32 v18, v241, v18, vcc
	ds_add_u32 v18, v206
	s_waitcnt lgkmcnt(7)
	v_fma_f32 v11, v11, v193, -v194
	v_cndmask_b32_e64 v159, -1.0, v11, s[72:73]
	v_cvt_i32_f32_e32 v19, v159
	v_cmp_ge_f32_e32 vcc, v159, v240
	v_min_i32_e32 v19, 0x3ff, v19
	v_lshl_add_u32 v19, v19, 2, s41
	v_cndmask_b32_e64 v19, v205, v19, s[72:73]
	v_cndmask_b32_e32 v19, v241, v19, vcc
	ds_add_u32 v19, v206
	s_waitcnt lgkmcnt(7)
	v_fma_f32 v12, v12, v193, -v194
	v_cndmask_b32_e64 v160, -1.0, v12, s[74:75]
	v_cvt_i32_f32_e32 v20, v160
	v_cmp_ge_f32_e32 vcc, v160, v240
	v_min_i32_e32 v20, 0x3ff, v20
	v_lshl_add_u32 v20, v20, 2, s41
	v_cndmask_b32_e64 v20, v205, v20, s[74:75]
	v_cndmask_b32_e32 v20, v241, v20, vcc
	ds_add_u32 v20, v206
	s_waitcnt lgkmcnt(7)
	v_fma_f32 v13, v13, v193, -v194
	v_cndmask_b32_e64 v161, -1.0, v13, s[76:77]
	v_cvt_i32_f32_e32 v21, v161
	v_cmp_ge_f32_e32 vcc, v161, v240
	v_min_i32_e32 v21, 0x3ff, v21
	v_lshl_add_u32 v21, v21, 2, s41
	v_cndmask_b32_e64 v21, v205, v21, s[76:77]
	v_cndmask_b32_e32 v21, v241, v21, vcc
	ds_add_u32 v21, v206
	s_waitcnt lgkmcnt(7)
	v_fma_f32 v14, v14, v193, -v194
	v_cndmask_b32_e64 v162, -1.0, v14, s[78:79]
	v_cvt_i32_f32_e32 v22, v162
	v_cmp_ge_f32_e32 vcc, v162, v240
	v_min_i32_e32 v22, 0x3ff, v22
	v_lshl_add_u32 v22, v22, 2, s41
	v_cndmask_b32_e64 v22, v205, v22, s[78:79]
	v_cndmask_b32_e32 v22, v241, v22, vcc
	ds_add_u32 v22, v206
	s_waitcnt lgkmcnt(7)
	v_fma_f32 v15, v15, v193, -v194
	v_cndmask_b32_e64 v163, -1.0, v15, s[80:81]
	v_cvt_i32_f32_e32 v23, v163
	v_cmp_ge_f32_e32 vcc, v163, v240
	v_min_i32_e32 v23, 0x3ff, v23
	v_lshl_add_u32 v23, v23, 2, s41
	v_cndmask_b32_e64 v23, v205, v23, s[80:81]
	v_cndmask_b32_e32 v23, v241, v23, vcc
	ds_add_u32 v23, v206
	s_branch .Lsel_B_done
; DI void selectA_item(const Params& p, int item, int next_item, char* lds, bf16x8 (&qf)[4], float (&wq)[16]) {
;     ...
; #pragma unroll
;     for (int i = 0; i < 64; ++i) { const int idx = gt + 128 * i; const float v = (idx < n) ? scq[idx] : lo; const float u = (v - lo) * scale; uu[i] = u;
;       if (big && idx < n) { int bb = (int)u; bb = bb > 1023 ? 1023 : bb; atomicAdd(&histq[bb], 1); } }
.Lsel_B_6_part:
	s_sub_i32 s2, s40, 0x1800
	ds_read_b32 v8, v181 offset:24576
	ds_read_b32 v9, v181 offset:25088
	ds_read_b32 v10, v181 offset:25600
	ds_read_b32 v11, v181 offset:26112
	ds_read_b32 v12, v181 offset:26624
	ds_read_b32 v13, v181 offset:27136
	ds_read_b32 v14, v181 offset:27648
	ds_read_b32 v15, v181 offset:28160
	v_cmp_gt_i32_e64 s[66:67], s2, v180
	s_sub_i32 s3, s2, 0x80
	v_cmp_gt_i32_e64 s[68:69], s3, v180
	s_sub_i32 s3, s2, 0x100
	v_cmp_gt_i32_e64 s[70:71], s3, v180
	s_sub_i32 s3, s2, 0x180
	v_cmp_gt_i32_e64 s[72:73], s3, v180
	s_sub_i32 s3, s2, 0x200
	v_cmp_gt_i32_e64 s[74:75], s3, v180
	s_sub_i32 s3, s2, 0x280
	v_cmp_gt_i32_e64 s[76:77], s3, v180
	s_sub_i32 s3, s2, 0x300
	v_cmp_gt_i32_e64 s[78:79], s3, v180
	s_sub_i32 s3, s2, 0x380
	v_cmp_gt_i32_e64 s[80:81], s3, v180
	s_waitcnt lgkmcnt(7)
	v_fma_f32 v8, v8, v193, -v194
	v_cndmask_b32_e64 v164, -1.0, v8, s[66:67]
	v_cvt_i32_f32_e32 v16, v164
	v_cmp_ge_f32_e32 vcc, v164, v240
	v_min_i32_e32 v16, 0x3ff, v16
	v_lshl_add_u32 v16, v16, 2, s41
	v_cndmask_b32_e64 v16, v205, v16, s[66:67]
	v_cndmask_b32_e32 v16, v241, v16, vcc
	ds_add_u32 v16, v206
	s_waitcnt lgkmcnt(7)
	v_fma_f32 v9, v9, v193, -v194
	v_cndmask_b32_e64 v165, -1.0, v9, s[68:69]
	v_cvt_i32_f32_e32 v17, v165
	v_cmp_ge_f32_e32 vcc, v165, v240
	v_min_i32_e32 v17, 0x3ff, v17
	v_lshl_add_u32 v17, v17, 2, s41
	v_cndmask_b32_e64 v17, v205, v17, s[68:69]
	v_cndmask_b32_e32 v17, v241, v17, vcc
	ds_add_u32 v17, v206
	s_waitcnt lgkmcnt(7)
	v_fma_f32 v10, v10, v193, -v194
	v_cndmask_b32_e64 v166, -1.0, v10, s[70:71]
	v_cvt_i32_f32_e32 v18, v166
	v_cmp_ge_f32_e32 vcc, v166, v240
	v_min_i32_e32 v18, 0x3ff, v18
	v_lshl_add_u32 v18, v18, 2, s41
	v_cndmask_b32_e64 v18, v205, v18, s[70:71]
	v_cndmask_b32_e32 v18, v241, v18, vcc
	ds_add_u32 v18, v206
	s_waitcnt lgkmcnt(7)
	v_fma_f32 v11, v11, v193, -v194
	v_cndmask_b32_e64 v167, -1.0, v11, s[72:73]
	v_cvt_i32_f32_e32 v19, v167
	v_cmp_ge_f32_e32 vcc, v167, v240
	v_min_i32_e32 v19, 0x3ff, v19
	v_lshl_add_u32 v19, v19, 2, s41
	v_cndmask_b32_e64 v19, v205, v19, s[72:73]
	v_cndmask_b32_e32 v19, v241, v19, vcc
	ds_add_u32 v19, v206
	s_waitcnt lgkmcnt(7)
	v_fma_f32 v12, v12, v193, -v194
	v_cndmask_b32_e64 v168, -1.0, v12, s[74:75]
	v_cvt_i32_f32_e32 v20, v168
	v_cmp_ge_f32_e32 vcc, v168, v240
	v_min_i32_e32 v20, 0x3ff, v20
	v_lshl_add_u32 v20, v20, 2, s41
	v_cndmask_b32_e64 v20, v205, v20, s[74:75]
	v_cndmask_b32_e32 v20, v241, v20, vcc
	ds_add_u32 v20, v206
	s_waitcnt lgkmcnt(7)
	v_fma_f32 v13, v13, v193, -v194
	v_cndmask_b32_e64 v169, -1.0, v13, s[76:77]
	v_cvt_i32_f32_e32 v21, v169
	v_cmp_ge_f32_e32 vcc, v169, v240
	v_min_i32_e32 v21, 0x3ff, v21
	v_lshl_add_u32 v21, v21, 2, s41
	v_cndmask_b32_e64 v21, v205, v21, s[76:77]
	v_cndmask_b32_e32 v21, v241, v21, vcc
	ds_add_u32 v21, v206
	s_waitcnt lgkmcnt(7)
	v_fma_f32 v14, v14, v193, -v194
	v_cndmask_b32_e64 v170, -1.0, v14, s[78:79]
	v_cvt_i32_f32_e32 v22, v170
	v_cmp_ge_f32_e32 vcc, v170, v240
	v_min_i32_e32 v22, 0x3ff, v22
	v_lshl_add_u32 v22, v22, 2, s41
	v_cndmask_b32_e64 v22, v205, v22, s[78:79]
	v_cndmask_b32_e32 v22, v241, v22, vcc
	ds_add_u32 v22, v206
	s_waitcnt lgkmcnt(7)
	v_fma_f32 v15, v15, v193, -v194
	v_cndmask_b32_e64 v171, -1.0, v15, s[80:81]
	v_cvt_i32_f32_e32 v23, v171
	v_cmp_ge_f32_e32 vcc, v171, v240
	v_min_i32_e32 v23, 0x3ff, v23
	v_lshl_add_u32 v23, v23, 2, s41
	v_cndmask_b32_e64 v23, v205, v23, s[80:81]
	v_cndmask_b32_e32 v23, v241, v23, vcc
	ds_add_u32 v23, v206
	s_branch .Lsel_B_done
.Lsel_B_7_part:
	s_sub_i32 s2, s40, 0x1c00
	ds_read_b32 v8, v181 offset:28672
	ds_read_b32 v9, v181 offset:29184
	ds_read_b32 v10, v181 offset:29696
	ds_read_b32 v11, v181 offset:30208
	ds_read_b32 v12, v181 offset:30720
	ds_read_b32 v13, v181 offset:31232
	ds_read_b32 v14, v181 offset:31744
	ds_read_b32 v15, v181 offset:32256
	v_cmp_gt_i32_e64 s[66:67], s2, v180
	s_sub_i32 s3, s2, 0x80
	v_cmp_gt_i32_e64 s[68:69], s3, v180
	s_sub_i32 s3, s2, 0x100
	v_cmp_gt_i32_e64 s[70:71], s3, v180
	s_sub_i32 s3, s2, 0x180
	v_cmp_gt_i32_e64 s[72:73], s3, v180
	s_sub_i32 s3, s2, 0x200
	v_cmp_gt_i32_e64 s[74:75], s3, v180
	s_sub_i32 s3, s2, 0x280
	v_cmp_gt_i32_e64 s[76:77], s3, v180
	s_sub_i32 s3, s2, 0x300
	v_cmp_gt_i32_e64 s[78:79], s3, v180
	s_sub_i32 s3, s2, 0x380
	v_cmp_gt_i32_e64 s[80:81], s3, v180
	s_waitcnt lgkmcnt(7)
	v_fma_f32 v8, v8, v193, -v194
	v_cndmask_b32_e64 v172, -1.0, v8, s[66:67]
	v_cvt_i32_f32_e32 v16, v172
	v_cmp_ge_f32_e32 vcc, v172, v240
	v_min_i32_e32 v16, 0x3ff, v16
	v_lshl_add_u32 v16, v16, 2, s41
	v_cndmask_b32_e64 v16, v205, v16, s[66:67]
	v_cndmask_b32_e32 v16, v241, v16, vcc
	ds_add_u32 v16, v206
	s_waitcnt lgkmcnt(7)
	v_fma_f32 v9, v9, v193, -v194
	v_cndmask_b32_e64 v173, -1.0, v9, s[68:69]
	v_cvt_i32_f32_e32 v17, v173
	v_cmp_ge_f32_e32 vcc, v173, v240
	v_min_i32_e32 v17, 0x3ff, v17
	v_lshl_add_u32 v17, v17, 2, s41
	v_cndmask_b32_e64 v17, v205, v17, s[68:69]
	v_cndmask_b32_e32 v17, v241, v17, vcc
	ds_add_u32 v17, v206
	s_waitcnt lgkmcnt(7)
	v_fma_f32 v10, v10, v193, -v194
	v_cndmask_b32_e64 v174, -1.0, v10, s[70:71]
	v_cvt_i32_f32_e32 v18, v174
	v_cmp_ge_f32_e32 vcc, v174, v240
	v_min_i32_e32 v18, 0x3ff, v18
	v_lshl_add_u32 v18, v18, 2, s41
	v_cndmask_b32_e64 v18, v205, v18, s[70:71]
	v_cndmask_b32_e32 v18, v241, v18, vcc
	ds_add_u32 v18, v206
	s_waitcnt lgkmcnt(7)
	v_fma_f32 v11, v11, v193, -v194
	v_cndmask_b32_e64 v175, -1.0, v11, s[72:73]
	v_cvt_i32_f32_e32 v19, v175
	v_cmp_ge_f32_e32 vcc, v175, v240
	v_min_i32_e32 v19, 0x3ff, v19
	v_lshl_add_u32 v19, v19, 2, s41
	v_cndmask_b32_e64 v19, v205, v19, s[72:73]
	v_cndmask_b32_e32 v19, v241, v19, vcc
	ds_add_u32 v19, v206
	s_waitcnt lgkmcnt(7)
	v_fma_f32 v12, v12, v193, -v194
	v_cndmask_b32_e64 v176, -1.0, v12, s[74:75]
	v_cvt_i32_f32_e32 v20, v176
	v_cmp_ge_f32_e32 vcc, v176, v240
	v_min_i32_e32 v20, 0x3ff, v20
	v_lshl_add_u32 v20, v20, 2, s41
	v_cndmask_b32_e64 v20, v205, v20, s[74:75]
	v_cndmask_b32_e32 v20, v241, v20, vcc
	ds_add_u32 v20, v206
	s_waitcnt lgkmcnt(7)
	v_fma_f32 v13, v13, v193, -v194
	v_cndmask_b32_e64 v177, -1.0, v13, s[76:77]
	v_cvt_i32_f32_e32 v21, v177
	v_cmp_ge_f32_e32 vcc, v177, v240
	v_min_i32_e32 v21, 0x3ff, v21
	v_lshl_add_u32 v21, v21, 2, s41
	v_cndmask_b32_e64 v21, v205, v21, s[76:77]
	v_cndmask_b32_e32 v21, v241, v21, vcc
	ds_add_u32 v21, v206
	s_waitcnt lgkmcnt(7)
	v_fma_f32 v14, v14, v193, -v194
	v_cndmask_b32_e64 v178, -1.0, v14, s[78:79]
	v_cvt_i32_f32_e32 v22, v178
	v_cmp_ge_f32_e32 vcc, v178, v240
	v_min_i32_e32 v22, 0x3ff, v22
	v_lshl_add_u32 v22, v22, 2, s41
	v_cndmask_b32_e64 v22, v205, v22, s[78:79]
	v_cndmask_b32_e32 v22, v241, v22, vcc
	ds_add_u32 v22, v206
	s_waitcnt lgkmcnt(7)
	v_fma_f32 v15, v15, v193, -v194
	v_cndmask_b32_e64 v179, -1.0, v15, s[80:81]
	v_cvt_i32_f32_e32 v23, v179
	v_cmp_ge_f32_e32 vcc, v179, v240
	v_min_i32_e32 v23, 0x3ff, v23
	v_lshl_add_u32 v23, v23, 2, s41
	v_cndmask_b32_e64 v23, v205, v23, s[80:81]
	v_cndmask_b32_e32 v23, v241, v23, vcc
	ds_add_u32 v23, v206
; DI void lds_barrier() { asm volatile("s_waitcnt lgkmcnt(0)" ::: "memory"); __builtin_amdgcn_s_barrier(); asm volatile("" ::: "memory"); }
; DI void selectA_item(const Params& p, int item, int next_item, char* lds, bf16x8 (&qf)[4], float (&wq)[16]) {
;     ...
;     typedef int i32x4 __attribute__((ext_vector_type(4)));
;     const i32x4 h0 = *(const i32x4*)(histq + gt * 8), h1 = *(const i32x4*)(histq + gt * 8 + 4);
;     const int hh[8] = {h0.x, h0.y, h0.z, h0.w, h1.x, h1.y, h1.z, h1.w};
;     int tot = 0;
; #pragma unroll
;     for (int k = 0; k < 8; ++k) tot += hh[k];
;     int inc = tot;
; #pragma unroll
;     for (int o = 1; o < 64; o <<= 1) { const int ux = __shfl_down(inc, o); if (lane + o < 64) inc += ux; }
;     if (lane == 0) misc[wid] = inc;
;     lds_barrier();
;     {
;       int above = inc - tot + (upper ? 0 : misc[wid + 1]);
;       if (big) {
; #pragma unroll
;         for (int k = 7; k >= 0; --k) { const int c = hh[k]; if (above < 256 && above + c >= 256) { mq[1] = gt * 8 + k; mq[2] = 256 - above; mq[3] = c; } above += c; }
;       }
;     }
;     lds_barrier();
;     const int bstar = mq[1], need = mq[2], cnt = mq[3];
;     const float flo = (float)bstar, fhi = (bstar >= 1023) ? INFINITY : (float)(bstar + 1);
.Lsel_B_done:
	s_waitcnt lgkmcnt(0)
	s_barrier
	s_cmp_lg_u32 s65, 0
	s_cbranch_scc1 .Lsel_D_skip
	v_sub_u32_e32 v0, 63, v183
	v_lshl_add_u32 v0, v0, 6, s41
	ds_read_b128 v[8:11], v0
	ds_read_b128 v[12:15], v0 offset:16
	ds_read_b128 v[16:19], v0 offset:32
	ds_read_b128 v[20:23], v0 offset:48
	s_waitcnt lgkmcnt(0)
	v_add3_u32 v24, v8, v9, v10
	v_add3_u32 v24, v24, v11, v12
	v_add3_u32 v24, v24, v13, v14
	v_add3_u32 v24, v24, v15, v16
	v_add3_u32 v24, v24, v17, v18
	v_add3_u32 v24, v24, v19, v20
	v_add3_u32 v24, v24, v21, v22
	v_add_u32_e32 v24, v24, v23
	v_mov_b32_e32 v25, v24
	s_nop 1
	v_add_u32_dpp v25, v25, v25 row_shr:1 row_mask:0xf bank_mask:0xf
	s_nop 1
	v_add_u32_dpp v25, v25, v25 row_shr:2 row_mask:0xf bank_mask:0xf
	s_nop 1
	v_add_u32_dpp v25, v25, v25 row_shr:4 row_mask:0xf bank_mask:0xf
	s_nop 1
	v_add_u32_dpp v25, v25, v25 row_shr:8 row_mask:0xf bank_mask:0xf
	s_nop 1
	v_add_u32_dpp v25, v25, v25 row_bcast:15 row_mask:0xa bank_mask:0xf
	s_nop 1
	v_add_u32_dpp v25, v25, v25 row_bcast:31 row_mask:0xc bank_mask:0xf
	s_nop 1
	v_sub_u32_e32 v26, v25, v24
	v_sub_u32_e32 v27, 0x100, v26
	v_mov_b32_e32 v30, -1
	v_mov_b32_e32 v31, 0
	v_mov_b32_e32 v50, 0
	v_add_u32_e32 v29, -1, v27
	v_cmp_lt_u32_e64 s[46:47], v29, v23
	v_sub_u32_e32 v28, v27, v23
	s_nop 0
	v_cndmask_b32_e64 v30, v30, 15, s[46:47]
	v_cndmask_b32_e64 v31, v31, v27, s[46:47]
	v_cndmask_b32_e64 v50, v50, v23, s[46:47]
	v_add_u32_e32 v29, -1, v28
	v_cmp_lt_u32_e64 s[48:49], v29, v22
	v_sub_u32_e32 v27, v28, v22
	s_nop 0
	v_cndmask_b32_e64 v30, v30, 14, s[48:49]
	v_cndmask_b32_e64 v31, v31, v28, s[48:49]
	v_cndmask_b32_e64 v50, v50, v22, s[48:49]
	v_add_u32_e32 v29, -1, v27
	v_cmp_lt_u32_e64 s[46:47], v29, v21
	v_sub_u32_e32 v28, v27, v21
	s_nop 0
	v_cndmask_b32_e64 v30, v30, 13, s[46:47]
	v_cndmask_b32_e64 v31, v31, v27, s[46:47]
	v_cndmask_b32_e64 v50, v50, v21, s[46:47]
	v_add_u32_e32 v29, -1, v28
	v_cmp_lt_u32_e64 s[48:49], v29, v20
	v_sub_u32_e32 v27, v28, v20
	s_nop 0
	v_cndmask_b32_e64 v30, v30, 12, s[48:49]
	v_cndmask_b32_e64 v31, v31, v28, s[48:49]
	v_cndmask_b32_e64 v50, v50, v20, s[48:49]
	v_add_u32_e32 v29, -1, v27
	v_cmp_lt_u32_e64 s[46:47], v29, v19
	v_sub_u32_e32 v28, v27, v19
	s_nop 0
	v_cndmask_b32_e64 v30, v30, 11, s[46:47]
	v_cndmask_b32_e64 v31, v31, v27, s[46:47]
	v_cndmask_b32_e64 v50, v50, v19, s[46:47]
	v_add_u32_e32 v29, -1, v28
	v_cmp_lt_u32_e64 s[48:49], v29, v18
	v_sub_u32_e32 v27, v28, v18
	s_nop 0
	v_cndmask_b32_e64 v30, v30, 10, s[48:49]
	v_cndmask_b32_e64 v31, v31, v28, s[48:49]
	v_cndmask_b32_e64 v50, v50, v18, s[48:49]
	v_add_u32_e32 v29, -1, v27
	v_cmp_lt_u32_e64 s[46:47], v29, v17
	v_sub_u32_e32 v28, v27, v17
	s_nop 0
	v_cndmask_b32_e64 v30, v30, 9, s[46:47]
	v_cndmask_b32_e64 v31, v31, v27, s[46:47]
	v_cndmask_b32_e64 v50, v50, v17, s[46:47]
	v_add_u32_e32 v29, -1, v28
	v_cmp_lt_u32_e64 s[48:49], v29, v16
	v_sub_u32_e32 v27, v28, v16
	s_nop 0
	v_cndmask_b32_e64 v30, v30, 8, s[48:49]
	v_cndmask_b32_e64 v31, v31, v28, s[48:49]
	v_cndmask_b32_e64 v50, v50, v16, s[48:49]
	v_add_u32_e32 v29, -1, v27
	v_cmp_lt_u32_e64 s[46:47], v29, v15
	v_sub_u32_e32 v28, v27, v15
	s_nop 0
	v_cndmask_b32_e64 v30, v30, 7, s[46:47]
	v_cndmask_b32_e64 v31, v31, v27, s[46:47]
	v_cndmask_b32_e64 v50, v50, v15, s[46:47]
	v_add_u32_e32 v29, -1, v28
	v_cmp_lt_u32_e64 s[48:49], v29, v14
	v_sub_u32_e32 v27, v28, v14
	s_nop 0
	v_cndmask_b32_e64 v30, v30, 6, s[48:49]
	v_cndmask_b32_e64 v31, v31, v28, s[48:49]
	v_cndmask_b32_e64 v50, v50, v14, s[48:49]
	v_add_u32_e32 v29, -1, v27
	v_cmp_lt_u32_e64 s[46:47], v29, v13
	v_sub_u32_e32 v28, v27, v13
	s_nop 0
	v_cndmask_b32_e64 v30, v30, 5, s[46:47]
	v_cndmask_b32_e64 v31, v31, v27, s[46:47]
	v_cndmask_b32_e64 v50, v50, v13, s[46:47]
	v_add_u32_e32 v29, -1, v28
	v_cmp_lt_u32_e64 s[48:49], v29, v12
	v_sub_u32_e32 v27, v28, v12
	s_nop 0
	v_cndmask_b32_e64 v30, v30, 4, s[48:49]
	v_cndmask_b32_e64 v31, v31, v28, s[48:49]
	v_cndmask_b32_e64 v50, v50, v12, s[48:49]
	v_add_u32_e32 v29, -1, v27
	v_cmp_lt_u32_e64 s[46:47], v29, v11
	v_sub_u32_e32 v28, v27, v11
	s_nop 0
	v_cndmask_b32_e64 v30, v30, 3, s[46:47]
	v_cndmask_b32_e64 v31, v31, v27, s[46:47]
	v_cndmask_b32_e64 v50, v50, v11, s[46:47]
	v_add_u32_e32 v29, -1, v28
	v_cmp_lt_u32_e64 s[48:49], v29, v10
	v_sub_u32_e32 v27, v28, v10
	s_nop 0
	v_cndmask_b32_e64 v30, v30, 2, s[48:49]
	v_cndmask_b32_e64 v31, v31, v28, s[48:49]
	v_cndmask_b32_e64 v50, v50, v10, s[48:49]
	v_add_u32_e32 v29, -1, v27
	v_cmp_lt_u32_e64 s[46:47], v29, v9
	v_sub_u32_e32 v28, v27, v9
	s_nop 0
	v_cndmask_b32_e64 v30, v30, 1, s[46:47]
	v_cndmask_b32_e64 v31, v31, v27, s[46:47]
	v_cndmask_b32_e64 v50, v50, v9, s[46:47]
	v_add_u32_e32 v29, -1, v28
	v_cmp_lt_u32_e64 s[48:49], v29, v8
	v_sub_u32_e32 v27, v28, v8
	s_nop 0
	v_cndmask_b32_e64 v30, v30, 0, s[48:49]
	v_cndmask_b32_e64 v31, v31, v28, s[48:49]
	v_cndmask_b32_e64 v50, v50, v8, s[48:49]
	v_cmp_le_i32_e32 vcc, 0, v30
	s_nop 3
	s_cmp_eq_u64 vcc, 0
	s_cbranch_scc1 .Lsel_fallback
	s_ff1_i32_b64 s64, vcc
	s_nop 0
	v_readlane_b32 s58, v30, s64
	v_readlane_b32 s59, v31, s64
	v_readlane_b32 s60, v50, s64
	s_sub_i32 s2, 63, s64
	s_lshl_b32 s2, s2, 4
	s_add_i32 s58, s58, s2
	s_cmp_gt_u32 s60, 0x80
	s_cbranch_scc1 .Lsel_fallback
	s_sub_i32 s61, 0x100, s59
	v_cvt_f32_i32_e32 v194, s58
	s_nop 0
	v_max_f32_e32 v194, v194, v240
	s_add_i32 s2, s58, 1
	v_cvt_f32_i32_e32 v195, s2
	s_cmp_ge_u32 s58, 0x3ff
	s_cbranch_scc0 .Lsel_fhi_ok
	v_mov_b32_e32 v195, 0x7f800000

; __device__ __forceinline__ unsigned xb_add(unsigned* p, unsigned v) { return __hip_atomic_fetch_add(p, v, __ATOMIC_RELAXED, __HIP_MEMORY_SCOPE_AGENT); }
; __device__ __forceinline__ void xcd_barrier(const XcdBarrier& b) {
;     ...
;             __builtin_amdgcn_fence(__ATOMIC_ACQUIRE, "agent");
;             xb_add(&bar[XB_XGEN(b.x)], 1u);
;             asm volatile("s_waitcnt vmcnt(0)" ::: "memory");
.LBB0_2573:
	s_or_b64 exec, exec, s[6:7]
	s_mov_b64 s[6:7], exec
	v_mbcnt_lo_u32_b32 v0, s6, 0
	v_mbcnt_hi_u32_b32 v0, s7, v0
	v_cmp_eq_u32_e32 vcc, 0, v0
	s_waitcnt vmcnt(0)
	buffer_inv sc1
	s_and_saveexec_b64 s[8:9], vcc
	s_cbranch_execz .LBB0_2575
	s_bcnt1_i32_b64 s6, s[6:7]
	v_mov_b32_e32 v0, 0x2000
	v_mov_b32_e32 v1, s6
	global_atomic_add v0, v1, s[2:3] offset:1024
	s_nop 0
.LBB0_2575:
	s_or_b64 exec, exec, s[8:9]
	s_waitcnt vmcnt(0)
